# pool: issue all 16 row loads back to back (addresses first, masks after) instead of 13 serialized round trips (stacked)
# speedup vs baseline: 1.0129x; 1.0060x over previous
.LBB0_235:
	v_add_u32_e32 v56, s9, v137
	v_mov_b32_e32 v131, v209
	s_ashr_i32 s11, s9, 31
	s_lshr_b32 s11, s11, 19
	s_add_i32 s11, s9, s11
	s_and_b32 s11, s11, 0xffffe000
	s_sub_i32 s11, s9, s11
	s_add_i32 s18, s11, -8
	s_add_i32 s0, s0, s3
	s_add_u32 s100, s84, s58
	s_addc_u32 s101, s85, 0
	v_add_u32_e32 v0, 0, v56
	v_max_i32_e32 v0, 8, v0
	v_add_u32_e32 v0, -8, v0
	v_min_u32_e32 v0, 0xffff, v0
	v_mul_u32_u24_e32 v208, 0xe00, v0
	v_lshl_add_u64 v[0:1], s[100:101], 0, v[208:209]
	v_lshl_add_u64 v[0:1], v[0:1], 0, v[130:131]
	global_load_dwordx4 v[0:3], v[0:1], off offset:1536
	v_add_u32_e32 v4, 2, v56
	v_max_i32_e32 v4, 8, v4
	v_add_u32_e32 v4, -8, v4
	v_min_u32_e32 v4, 0xffff, v4
	v_mul_u32_u24_e32 v208, 0xe00, v4
	v_lshl_add_u64 v[4:5], s[100:101], 0, v[208:209]
	v_lshl_add_u64 v[4:5], v[4:5], 0, v[130:131]
	global_load_dwordx4 v[4:7], v[4:5], off offset:1536
	v_add_u32_e32 v8, 4, v56
	v_max_i32_e32 v8, 8, v8
	v_add_u32_e32 v8, -8, v8
	v_min_u32_e32 v8, 0xffff, v8
	v_mul_u32_u24_e32 v208, 0xe00, v8
	v_lshl_add_u64 v[8:9], s[100:101], 0, v[208:209]
	v_lshl_add_u64 v[8:9], v[8:9], 0, v[130:131]
	global_load_dwordx4 v[8:11], v[8:9], off offset:1536
	v_add_u32_e32 v12, 6, v56
	v_max_i32_e32 v12, 8, v12
	v_add_u32_e32 v12, -8, v12
	v_min_u32_e32 v12, 0xffff, v12
	v_mul_u32_u24_e32 v208, 0xe00, v12
	v_lshl_add_u64 v[12:13], s[100:101], 0, v[208:209]
	v_lshl_add_u64 v[12:13], v[12:13], 0, v[130:131]
	global_load_dwordx4 v[12:15], v[12:13], off offset:1536
	v_add_u32_e32 v16, 8, v56
	v_max_i32_e32 v16, 8, v16
	v_add_u32_e32 v16, -8, v16
	v_min_u32_e32 v16, 0xffff, v16
	v_mul_u32_u24_e32 v208, 0xe00, v16
	v_lshl_add_u64 v[16:17], s[100:101], 0, v[208:209]
	v_lshl_add_u64 v[16:17], v[16:17], 0, v[130:131]
	global_load_dwordx4 v[16:19], v[16:17], off offset:1536
	v_add_u32_e32 v20, 10, v56
	v_max_i32_e32 v20, 8, v20
	v_add_u32_e32 v20, -8, v20
	v_min_u32_e32 v20, 0xffff, v20
	v_mul_u32_u24_e32 v208, 0xe00, v20
	v_lshl_add_u64 v[20:21], s[100:101], 0, v[208:209]
	v_lshl_add_u64 v[20:21], v[20:21], 0, v[130:131]
	global_load_dwordx4 v[20:23], v[20:21], off offset:1536
	v_add_u32_e32 v24, 12, v56
	v_max_i32_e32 v24, 8, v24
	v_add_u32_e32 v24, -8, v24
	v_min_u32_e32 v24, 0xffff, v24
	v_mul_u32_u24_e32 v208, 0xe00, v24
	v_lshl_add_u64 v[24:25], s[100:101], 0, v[208:209]
	v_lshl_add_u64 v[24:25], v[24:25], 0, v[130:131]
	global_load_dwordx4 v[24:27], v[24:25], off offset:1536
	v_add_u32_e32 v28, 14, v56
	v_max_i32_e32 v28, 8, v28
	v_add_u32_e32 v28, -8, v28
	v_min_u32_e32 v28, 0xffff, v28
	v_mul_u32_u24_e32 v208, 0xe00, v28
	v_lshl_add_u64 v[28:29], s[100:101], 0, v[208:209]
	v_lshl_add_u64 v[28:29], v[28:29], 0, v[130:131]
	global_load_dwordx4 v[28:31], v[28:29], off offset:1536
	v_add_u32_e32 v32, 16, v56
	v_max_i32_e32 v32, 8, v32
	v_add_u32_e32 v32, -8, v32
	v_min_u32_e32 v32, 0xffff, v32
	v_mul_u32_u24_e32 v208, 0xe00, v32
	v_lshl_add_u64 v[32:33], s[100:101], 0, v[208:209]
	v_lshl_add_u64 v[32:33], v[32:33], 0, v[130:131]
	global_load_dwordx4 v[32:35], v[32:33], off offset:1536
	v_add_u32_e32 v36, 18, v56
	v_max_i32_e32 v36, 8, v36
	v_add_u32_e32 v36, -8, v36
	v_min_u32_e32 v36, 0xffff, v36
	v_mul_u32_u24_e32 v208, 0xe00, v36
	v_lshl_add_u64 v[36:37], s[100:101], 0, v[208:209]
	v_lshl_add_u64 v[36:37], v[36:37], 0, v[130:131]
	global_load_dwordx4 v[36:39], v[36:37], off offset:1536
	v_add_u32_e32 v40, 20, v56
	v_max_i32_e32 v40, 8, v40
	v_add_u32_e32 v40, -8, v40
	v_min_u32_e32 v40, 0xffff, v40
	v_mul_u32_u24_e32 v208, 0xe00, v40
	v_lshl_add_u64 v[40:41], s[100:101], 0, v[208:209]
	v_lshl_add_u64 v[40:41], v[40:41], 0, v[130:131]
	global_load_dwordx4 v[40:43], v[40:41], off offset:1536
	v_add_u32_e32 v44, 22, v56
	v_max_i32_e32 v44, 8, v44
	v_add_u32_e32 v44, -8, v44
	v_min_u32_e32 v44, 0xffff, v44
	v_mul_u32_u24_e32 v208, 0xe00, v44
	v_lshl_add_u64 v[44:45], s[100:101], 0, v[208:209]
	v_lshl_add_u64 v[44:45], v[44:45], 0, v[130:131]
	global_load_dwordx4 v[44:47], v[44:45], off offset:1536
	v_add_u32_e32 v48, 24, v56
	v_max_i32_e32 v48, 8, v48
	v_add_u32_e32 v48, -8, v48
	v_min_u32_e32 v48, 0xffff, v48
	v_mul_u32_u24_e32 v208, 0xe00, v48
	v_lshl_add_u64 v[48:49], s[100:101], 0, v[208:209]
	v_lshl_add_u64 v[48:49], v[48:49], 0, v[130:131]
	global_load_dwordx4 v[48:51], v[48:49], off offset:1536
	v_add_u32_e32 v52, 26, v56
	v_max_i32_e32 v52, 8, v52
	v_add_u32_e32 v52, -8, v52
	v_min_u32_e32 v52, 0xffff, v52
	v_mul_u32_u24_e32 v208, 0xe00, v52
	v_lshl_add_u64 v[52:53], s[100:101], 0, v[208:209]
	v_lshl_add_u64 v[52:53], v[52:53], 0, v[130:131]
	global_load_dwordx4 v[52:55], v[52:53], off offset:1536
	v_add_u32_e32 v58, 28, v56
	v_max_i32_e32 v58, 8, v58
	v_add_u32_e32 v58, -8, v58
	v_min_u32_e32 v58, 0xffff, v58
	v_mul_u32_u24_e32 v208, 0xe00, v58
	v_lshl_add_u64 v[58:59], s[100:101], 0, v[208:209]
	v_lshl_add_u64 v[58:59], v[58:59], 0, v[130:131]
	global_load_dwordx4 v[58:61], v[58:59], off offset:1536
	v_add_u32_e32 v62, 30, v56
	v_max_i32_e32 v62, 8, v62
	v_add_u32_e32 v62, -8, v62
	v_min_u32_e32 v62, 0xffff, v62
	v_mul_u32_u24_e32 v208, 0xe00, v62
	v_lshl_add_u64 v[62:63], s[100:101], 0, v[208:209]
	v_lshl_add_u64 v[62:63], v[62:63], 0, v[130:131]
	global_load_dwordx4 v[62:65], v[62:63], off offset:1536
	s_cmpk_lt_u32 s18, 0x2000
	s_cselect_b64 vcc, -1, 0
	s_waitcnt vmcnt(15)
	v_cndmask_b32_e32 v3, 0, v3, vcc
	v_cndmask_b32_e32 v2, 0, v2, vcc
	v_cndmask_b32_e32 v1, 0, v1, vcc
	v_cndmask_b32_e32 v0, 0, v0, vcc
	s_waitcnt vmcnt(14)
	v_cndmask_b32_e32 v7, 0, v7, vcc
	v_cndmask_b32_e32 v6, 0, v6, vcc
	v_cndmask_b32_e32 v5, 0, v5, vcc
	v_cndmask_b32_e32 v4, 0, v4, vcc
	s_waitcnt vmcnt(13)
	v_cndmask_b32_e32 v11, 0, v11, vcc
	v_cndmask_b32_e32 v10, 0, v10, vcc
	v_cndmask_b32_e32 v9, 0, v9, vcc
	v_cndmask_b32_e32 v8, 0, v8, vcc
	s_waitcnt vmcnt(12)
	v_cndmask_b32_e32 v15, 0, v15, vcc
	v_cndmask_b32_e32 v14, 0, v14, vcc
	v_cndmask_b32_e32 v13, 0, v13, vcc
	v_cndmask_b32_e32 v12, 0, v12, vcc
	s_cmp_gt_i32 s11, -1
	s_cselect_b64 vcc, -1, 0
	s_waitcnt vmcnt(11)
	v_cndmask_b32_e32 v19, 0, v19, vcc
	v_cndmask_b32_e32 v18, 0, v18, vcc
	v_cndmask_b32_e32 v17, 0, v17, vcc
	v_cndmask_b32_e32 v16, 0, v16, vcc
	v_add_u32_e32 v206, s18, v138
	v_cmp_gt_u32_e32 vcc, s15, v206
	s_waitcnt vmcnt(10)
	s_nop 0
	v_cndmask_b32_e32 v23, 0, v23, vcc
	v_cndmask_b32_e32 v22, 0, v22, vcc
	v_cndmask_b32_e32 v21, 0, v21, vcc
	v_cndmask_b32_e32 v20, 0, v20, vcc
	v_add_u32_e32 v206, s18, v139
	v_cmp_gt_u32_e32 vcc, s15, v206
	s_waitcnt vmcnt(9)
	s_nop 0
	v_cndmask_b32_e32 v27, 0, v27, vcc
	v_cndmask_b32_e32 v26, 0, v26, vcc
	v_cndmask_b32_e32 v25, 0, v25, vcc
	v_cndmask_b32_e32 v24, 0, v24, vcc
	v_add_u32_e32 v206, s18, v140
	v_cmp_gt_u32_e32 vcc, s15, v206
	s_waitcnt vmcnt(8)
	s_nop 0
	v_cndmask_b32_e32 v31, 0, v31, vcc
	v_cndmask_b32_e32 v30, 0, v30, vcc
	v_cndmask_b32_e32 v29, 0, v29, vcc
	v_cndmask_b32_e32 v28, 0, v28, vcc
	v_add_u32_e32 v206, s18, v141
	v_cmp_gt_u32_e32 vcc, s15, v206
	s_waitcnt vmcnt(7)
	s_nop 0
	v_cndmask_b32_e32 v35, 0, v35, vcc
	v_cndmask_b32_e32 v34, 0, v34, vcc
	v_cndmask_b32_e32 v33, 0, v33, vcc
	v_cndmask_b32_e32 v32, 0, v32, vcc
	v_add_u32_e32 v206, s18, v142
	v_cmp_gt_u32_e32 vcc, s15, v206
	s_waitcnt vmcnt(6)
	s_nop 0
	v_cndmask_b32_e32 v39, 0, v39, vcc
	v_cndmask_b32_e32 v38, 0, v38, vcc
	v_cndmask_b32_e32 v37, 0, v37, vcc
	v_cndmask_b32_e32 v36, 0, v36, vcc
	v_add_u32_e32 v206, s18, v143
	v_cmp_gt_u32_e32 vcc, s15, v206
	s_waitcnt vmcnt(5)
	s_nop 0
	v_cndmask_b32_e32 v43, 0, v43, vcc
	v_cndmask_b32_e32 v42, 0, v42, vcc
	v_cndmask_b32_e32 v41, 0, v41, vcc
	v_cndmask_b32_e32 v40, 0, v40, vcc
	v_add_u32_e32 v206, s18, v144
	v_cmp_gt_u32_e32 vcc, s15, v206
	s_waitcnt vmcnt(4)
	s_nop 0
	v_cndmask_b32_e32 v47, 0, v47, vcc
	v_cndmask_b32_e32 v46, 0, v46, vcc
	v_cndmask_b32_e32 v45, 0, v45, vcc
	v_cndmask_b32_e32 v44, 0, v44, vcc
	v_add_u32_e32 v206, s18, v145
	v_cmp_gt_u32_e32 vcc, s15, v206
	s_waitcnt vmcnt(3)
	s_nop 0
	v_cndmask_b32_e32 v51, 0, v51, vcc
	v_cndmask_b32_e32 v50, 0, v50, vcc
	v_cndmask_b32_e32 v49, 0, v49, vcc
	v_cndmask_b32_e32 v48, 0, v48, vcc
	v_add_u32_e32 v206, s18, v146
	v_cmp_gt_u32_e32 vcc, s15, v206
	s_waitcnt vmcnt(2)
	s_nop 0
	v_cndmask_b32_e32 v55, 0, v55, vcc
	v_cndmask_b32_e32 v54, 0, v54, vcc
	v_cndmask_b32_e32 v53, 0, v53, vcc
	v_cndmask_b32_e32 v52, 0, v52, vcc
	v_add_u32_e32 v206, s18, v147
	v_cmp_gt_u32_e32 vcc, s15, v206
	s_waitcnt vmcnt(1)
	s_nop 0
	v_cndmask_b32_e32 v61, 0, v61, vcc
	v_cndmask_b32_e32 v60, 0, v60, vcc
	v_cndmask_b32_e32 v59, 0, v59, vcc
	v_cndmask_b32_e32 v58, 0, v58, vcc
	v_add_u32_e32 v206, s18, v148
	v_cmp_gt_u32_e32 vcc, s15, v206
	s_waitcnt vmcnt(0)
	s_nop 0
	v_cndmask_b32_e32 v65, 0, v65, vcc
	v_cndmask_b32_e32 v64, 0, v64, vcc
	v_cndmask_b32_e32 v63, 0, v63, vcc
	v_cndmask_b32_e32 v62, 0, v62, vcc
	v_or_b32_e32 v56, s11, v136
	ds_write_b128 v150, v[0:3]
	ds_write_b128 v150, v[4:7] offset:1056
	ds_write_b128 v150, v[8:11] offset:2112
	ds_write_b128 v150, v[12:15] offset:3168
	ds_write_b128 v150, v[16:19] offset:4224
	ds_write_b128 v150, v[20:23] offset:5280
	ds_write_b128 v150, v[24:27] offset:6336
	ds_write_b128 v150, v[28:31] offset:7392
	ds_write_b128 v150, v[32:35] offset:8448
	ds_write_b128 v150, v[36:39] offset:9504
	ds_write_b128 v150, v[40:43] offset:10560
	ds_write_b128 v150, v[44:47] offset:11616
	ds_write_b128 v150, v[48:51] offset:12672
	ds_write_b128 v150, v[52:55] offset:13728
	ds_write_b128 v150, v[58:61] offset:14784
	ds_write_b128 v150, v[62:65] offset:15840
	v_add_u32_e32 v0, s9, v136
	v_ashrrev_i32_e32 v1, 31, v0
	v_lshlrev_b64 v[134:135], 11, v[0:1]
	v_max_i32_e32 v0, 1, v56
	v_min_i32_e32 v1, 0x1fff, v56
	v_sub_u32_e32 v0, v1, v0
	v_add_u32_e32 v0, 2, v0
	v_cvt_f32_i32_e32 v0, v0
	s_waitcnt lgkmcnt(0)
	s_add_i32 s9, s9, s17
	s_cmpk_lt_i32 s0, 0x1000
	v_div_scale_f32 v1, s[18:19], v0, v0, 1.0
	v_rcp_f32_e32 v2, v1
	s_nop 0
	v_fma_f32 v3, -v1, v2, 1.0
	v_fmac_f32_e32 v2, v3, v2
	v_div_scale_f32 v3, vcc, 1.0, v0, 1.0
	v_mul_f32_e32 v4, v3, v2
	v_fma_f32 v5, -v1, v4, v3
	v_fmac_f32_e32 v4, v5, v2
	v_fma_f32 v1, -v1, v4, v3
	v_div_fmas_f32 v1, v1, v2, v4
	v_div_fixup_f32 v20, v1, v0, 1.0
	ds_read_b128 v[0:3], v149 offset:3696
	s_waitcnt lgkmcnt(0)
	v_lshlrev_b32_e32 v4, 16, v0
	v_and_b32_e32 v0, 0xffff0000, v0
	v_lshlrev_b32_e32 v5, 16, v1
	v_and_b32_e32 v1, 0xffff0000, v1
	v_lshlrev_b32_e32 v6, 16, v2
	v_and_b32_e32 v2, 0xffff0000, v2
	v_lshlrev_b32_e32 v7, 16, v3
	v_and_b32_e32 v3, 0xffff0000, v3
	v_add_f32_e32 v8, 0, v0
	v_add_f32_e32 v9, 0, v1
	v_add_f32_e32 v10, 0, v2
	v_add_f32_e32 v11, 0, v3
	ds_read_b128 v[0:3], v149 offset:4224
	v_add_f32_e32 v4, 0, v4
	v_add_f32_e32 v5, 0, v5
	v_add_f32_e32 v6, 0, v6
	v_add_f32_e32 v7, 0, v7
	s_waitcnt lgkmcnt(0)
	v_lshlrev_b32_e32 v12, 16, v0
	v_and_b32_e32 v0, 0xffff0000, v0
	v_lshlrev_b32_e32 v13, 16, v1
	v_and_b32_e32 v1, 0xffff0000, v1
	v_lshlrev_b32_e32 v14, 16, v2
	v_and_b32_e32 v2, 0xffff0000, v2
	v_lshlrev_b32_e32 v15, 16, v3
	v_and_b32_e32 v3, 0xffff0000, v3
	v_add_f32_e32 v8, v8, v0
	v_add_f32_e32 v9, v9, v1
	v_add_f32_e32 v10, v10, v2
	v_add_f32_e32 v11, v11, v3
	v_add_f32_e32 v4, v4, v12
	v_add_f32_e32 v5, v5, v13
	v_add_f32_e32 v6, v6, v14
	v_add_f32_e32 v7, v7, v15
	v_fma_f32 v0, v20, v8, -v0
	v_fma_f32 v1, v20, v9, -v1
	v_fma_f32 v2, v20, v10, -v2
	v_fma_f32 v3, v20, v11, -v3
	v_fma_f32 v4, v20, v4, -v12
	v_fma_f32 v5, v20, v5, -v13
	v_fma_f32 v6, v20, v6, -v14
	v_fma_f32 v7, v20, v7, -v15
	v_cvt_pk_bf16_f32 v0, v4, v0
	v_cvt_pk_bf16_f32 v1, v5, v1
	v_cvt_pk_bf16_f32 v2, v6, v2
	v_cvt_pk_bf16_f32 v3, v7, v3
	global_load_dwordx4 v[12:15], v[74:75], off
	global_load_dwordx4 v[4:7], v[72:73], off
	global_load_dwordx4 v[8:11], v[72:73], off offset:2048
	s_waitcnt vmcnt(2)
	v_mfma_f32_16x16x32_bf16 v[16:19], v[12:15], v[0:3], 0
	global_load_dwordx4 v[12:15], v[76:77], off
	s_waitcnt vmcnt(2)
	v_mfma_f32_16x16x32_bf16 v[4:7], v[4:7], v[0:3], 0
	s_waitcnt vmcnt(1)
	v_mfma_f32_16x16x32_bf16 v[8:11], v[8:11], v[0:3], 0
	s_waitcnt vmcnt(0)
	v_mfma_f32_16x16x32_bf16 v[0:3], v[12:15], v[0:3], 0
	ds_read_b128 v[12:15], v149 offset:3760
	s_waitcnt lgkmcnt(0)
	v_lshlrev_b32_e32 v21, 16, v12
	v_and_b32_e32 v12, 0xffff0000, v12
	v_lshlrev_b32_e32 v22, 16, v13
	v_and_b32_e32 v13, 0xffff0000, v13
	v_lshlrev_b32_e32 v23, 16, v14
	v_and_b32_e32 v14, 0xffff0000, v14
	v_lshlrev_b32_e32 v24, 16, v15
	v_and_b32_e32 v15, 0xffff0000, v15
	v_add_f32_e32 v25, 0, v12
	v_add_f32_e32 v26, 0, v13
	v_add_f32_e32 v27, 0, v14
	v_add_f32_e32 v28, 0, v15
	ds_read_b128 v[12:15], v149 offset:4288
	v_add_f32_e32 v21, 0, v21
	v_add_f32_e32 v22, 0, v22
	v_add_f32_e32 v23, 0, v23
	v_add_f32_e32 v24, 0, v24
	s_waitcnt lgkmcnt(0)
	v_lshlrev_b32_e32 v29, 16, v12
	v_and_b32_e32 v12, 0xffff0000, v12
	v_lshlrev_b32_e32 v30, 16, v13
	v_and_b32_e32 v13, 0xffff0000, v13
	v_lshlrev_b32_e32 v31, 16, v14
	v_and_b32_e32 v14, 0xffff0000, v14
	v_lshlrev_b32_e32 v32, 16, v15
	v_and_b32_e32 v15, 0xffff0000, v15
	v_add_f32_e32 v21, v21, v29
	v_add_f32_e32 v25, v25, v12
	v_add_f32_e32 v22, v22, v30
	v_add_f32_e32 v26, v26, v13
	v_add_f32_e32 v23, v23, v31
	v_add_f32_e32 v27, v27, v14
	v_add_f32_e32 v28, v28, v15
	v_add_f32_e32 v24, v24, v32
	v_fma_f32 v21, v20, v21, -v29
	v_fma_f32 v12, v20, v25, -v12
	v_fma_f32 v22, v20, v22, -v30
	v_fma_f32 v13, v20, v26, -v13
	v_fma_f32 v23, v20, v23, -v31
	v_fma_f32 v14, v20, v27, -v14
	v_fma_f32 v15, v20, v28, -v15
	v_fma_f32 v24, v20, v24, -v32
	v_cvt_pk_bf16_f32 v20, v21, v12
	v_cvt_pk_bf16_f32 v21, v22, v13
	v_cvt_pk_bf16_f32 v22, v23, v14
	v_cvt_pk_bf16_f32 v23, v24, v15
	s_waitcnt vmcnt(0)
	v_mfma_f32_16x16x32_bf16 v[12:15], v[166:169], v[20:23], v[4:7]
	s_nop 2
	s_waitcnt vmcnt(0)
	v_mfma_f32_16x16x32_bf16 v[8:11], v[170:173], v[20:23], v[8:11]
	s_waitcnt vmcnt(0)
	v_mfma_f32_16x16x32_bf16 v[4:7], v[174:177], v[20:23], v[16:19]
	s_nop 2
	s_waitcnt vmcnt(0)
	v_mfma_f32_16x16x32_bf16 v[0:3], v[178:181], v[20:23], v[0:3]
	v_max_i32_e32 v16, 2, v56
	v_min_i32_e32 v17, 0x1ffe, v56
	v_sub_u32_e32 v16, v17, v16
	v_add_u32_e32 v16, 4, v16
	v_cvt_f32_i32_e32 v16, v16
	v_div_scale_f32 v17, s[18:19], v16, v16, 1.0
	v_rcp_f32_e32 v18, v17
	s_nop 0
	v_fma_f32 v19, -v17, v18, 1.0
	v_fmac_f32_e32 v18, v19, v18
	v_div_scale_f32 v19, vcc, 1.0, v16, 1.0
	v_mul_f32_e32 v20, v19, v18
	v_fma_f32 v21, -v17, v20, v19
	v_fmac_f32_e32 v20, v21, v18
	v_fma_f32 v17, -v17, v20, v19
	v_div_fmas_f32 v17, v17, v18, v20
	v_div_fixup_f32 v36, v17, v16, 1.0
	ds_read_b128 v[16:19], v149 offset:3296
	s_waitcnt lgkmcnt(0)
	v_lshlrev_b32_e32 v20, 16, v16
	v_and_b32_e32 v16, 0xffff0000, v16
	v_lshlrev_b32_e32 v21, 16, v17
	v_and_b32_e32 v17, 0xffff0000, v17
	v_lshlrev_b32_e32 v22, 16, v18
	v_and_b32_e32 v18, 0xffff0000, v18
	v_lshlrev_b32_e32 v23, 16, v19
	v_and_b32_e32 v19, 0xffff0000, v19
	v_add_f32_e32 v24, 0, v16
	v_add_f32_e32 v25, 0, v17
	v_add_f32_e32 v26, 0, v18
	v_add_f32_e32 v27, 0, v19
	ds_read_b128 v[16:19], v149 offset:3824
	v_add_f32_e32 v20, 0, v20
	v_add_f32_e32 v21, 0, v21
	v_add_f32_e32 v22, 0, v22
	v_add_f32_e32 v23, 0, v23
	s_waitcnt lgkmcnt(0)
	v_lshlrev_b32_e32 v28, 16, v16
	v_and_b32_e32 v16, 0xffff0000, v16
	v_lshlrev_b32_e32 v29, 16, v17
	v_and_b32_e32 v17, 0xffff0000, v17
	v_lshlrev_b32_e32 v30, 16, v18
	v_and_b32_e32 v18, 0xffff0000, v18
	v_lshlrev_b32_e32 v31, 16, v19
	v_and_b32_e32 v19, 0xffff0000, v19
	v_add_f32_e32 v24, v24, v16
	v_add_f32_e32 v25, v25, v17
	v_add_f32_e32 v26, v26, v18
	v_add_f32_e32 v27, v27, v19
	ds_read_b128 v[16:19], v149 offset:4352
	v_add_f32_e32 v20, v20, v28
	v_add_f32_e32 v21, v21, v29
	v_add_f32_e32 v22, v22, v30
	v_add_f32_e32 v23, v23, v31
	s_waitcnt lgkmcnt(0)
	v_lshlrev_b32_e32 v28, 16, v16
	v_and_b32_e32 v29, 0xffff0000, v16
	v_lshlrev_b32_e32 v30, 16, v17
	v_and_b32_e32 v31, 0xffff0000, v17
	v_lshlrev_b32_e32 v32, 16, v18
	v_and_b32_e32 v33, 0xffff0000, v18
	v_lshlrev_b32_e32 v34, 16, v19
	v_and_b32_e32 v35, 0xffff0000, v19
	ds_read_b128 v[16:19], v149 offset:4880
	v_add_f32_e32 v24, v24, v29
	v_add_f32_e32 v25, v25, v31
	v_add_f32_e32 v26, v26, v33
	v_add_f32_e32 v27, v27, v35
	s_waitcnt lgkmcnt(0)
	v_lshlrev_b32_e32 v37, 16, v16
	v_and_b32_e32 v16, 0xffff0000, v16
	v_lshlrev_b32_e32 v38, 16, v17
	v_and_b32_e32 v17, 0xffff0000, v17
	v_lshlrev_b32_e32 v39, 16, v18
	v_and_b32_e32 v18, 0xffff0000, v18
	v_lshlrev_b32_e32 v40, 16, v19
	v_and_b32_e32 v19, 0xffff0000, v19
	v_add_f32_e32 v20, v20, v28
	v_add_f32_e32 v21, v21, v30
	v_add_f32_e32 v22, v22, v32
	v_add_f32_e32 v23, v23, v34
	v_add_f32_e32 v16, v24, v16
	v_add_f32_e32 v17, v25, v17
	v_add_f32_e32 v18, v26, v18
	v_add_f32_e32 v19, v27, v19
	v_add_f32_e32 v20, v20, v37
	v_add_f32_e32 v21, v21, v38
	v_add_f32_e32 v22, v22, v39
	v_add_f32_e32 v23, v23, v40
	v_fma_f32 v16, v36, v16, -v29
	v_fma_f32 v17, v36, v17, -v31
	v_fma_f32 v18, v36, v18, -v33
	v_fma_f32 v19, v36, v19, -v35
	v_fma_f32 v20, v36, v20, -v28
	v_fma_f32 v21, v36, v21, -v30
	v_fma_f32 v22, v36, v22, -v32
	v_fma_f32 v23, v36, v23, -v34
	v_cvt_pk_bf16_f32 v16, v20, v16
	v_cvt_pk_bf16_f32 v17, v21, v17
	v_cvt_pk_bf16_f32 v18, v22, v18
	v_cvt_pk_bf16_f32 v19, v23, v19
	global_load_dwordx4 v[28:31], v[86:87], off
	global_load_dwordx4 v[20:23], v[82:83], off
	global_load_dwordx4 v[24:27], v[84:85], off
	s_waitcnt vmcnt(2)
	v_mfma_f32_16x16x32_bf16 v[32:35], v[28:31], v[16:19], 0
	global_load_dwordx4 v[28:31], v[88:89], off
	s_waitcnt vmcnt(2)
	v_mfma_f32_16x16x32_bf16 v[20:23], v[20:23], v[16:19], 0
	s_waitcnt vmcnt(1)
	v_mfma_f32_16x16x32_bf16 v[24:27], v[24:27], v[16:19], 0
	s_waitcnt vmcnt(0)
	v_mfma_f32_16x16x32_bf16 v[16:19], v[28:31], v[16:19], 0
	ds_read_b128 v[28:31], v149 offset:3360
	s_waitcnt lgkmcnt(0)
	v_lshlrev_b32_e32 v37, 16, v28
	v_and_b32_e32 v28, 0xffff0000, v28
	v_lshlrev_b32_e32 v38, 16, v29
	v_and_b32_e32 v29, 0xffff0000, v29
	v_lshlrev_b32_e32 v39, 16, v30
	v_and_b32_e32 v30, 0xffff0000, v30
	v_lshlrev_b32_e32 v40, 16, v31
	v_and_b32_e32 v31, 0xffff0000, v31
	v_add_f32_e32 v41, 0, v28
	v_add_f32_e32 v42, 0, v29
	v_add_f32_e32 v43, 0, v30
	v_add_f32_e32 v44, 0, v31
	ds_read_b128 v[28:31], v149 offset:3888
	v_add_f32_e32 v37, 0, v37
	v_add_f32_e32 v38, 0, v38
	v_add_f32_e32 v39, 0, v39
	v_add_f32_e32 v40, 0, v40
	s_waitcnt lgkmcnt(0)
	v_lshlrev_b32_e32 v45, 16, v28
	v_and_b32_e32 v28, 0xffff0000, v28
	v_lshlrev_b32_e32 v46, 16, v29
	v_and_b32_e32 v29, 0xffff0000, v29
	v_lshlrev_b32_e32 v47, 16, v30
	v_and_b32_e32 v30, 0xffff0000, v30
	v_lshlrev_b32_e32 v48, 16, v31
	v_and_b32_e32 v31, 0xffff0000, v31
	v_add_f32_e32 v41, v41, v28
	v_add_f32_e32 v42, v42, v29
	v_add_f32_e32 v43, v43, v30
	v_add_f32_e32 v44, v44, v31
	ds_read_b128 v[28:31], v149 offset:4416
	v_add_f32_e32 v37, v37, v45
	v_add_f32_e32 v38, v38, v46
	v_add_f32_e32 v39, v39, v47
	v_add_f32_e32 v40, v40, v48
	s_waitcnt lgkmcnt(0)
	v_lshlrev_b32_e32 v45, 16, v28
	v_and_b32_e32 v46, 0xffff0000, v28
	v_lshlrev_b32_e32 v47, 16, v29
	v_and_b32_e32 v48, 0xffff0000, v29
	v_lshlrev_b32_e32 v49, 16, v30
	v_and_b32_e32 v50, 0xffff0000, v30
	v_lshlrev_b32_e32 v51, 16, v31
	v_and_b32_e32 v52, 0xffff0000, v31
	ds_read_b128 v[28:31], v149 offset:4944
	v_add_f32_e32 v37, v37, v45
	v_add_f32_e32 v41, v41, v46
	v_add_f32_e32 v38, v38, v47
	v_add_f32_e32 v42, v42, v48
	v_add_f32_e32 v39, v39, v49
	v_add_f32_e32 v43, v43, v50
	v_add_f32_e32 v44, v44, v52
	s_waitcnt lgkmcnt(0)
	v_lshlrev_b32_e32 v53, 16, v28
	v_and_b32_e32 v28, 0xffff0000, v28
	v_lshlrev_b32_e32 v54, 16, v29
	v_and_b32_e32 v29, 0xffff0000, v29
	v_lshlrev_b32_e32 v55, 16, v30
	v_and_b32_e32 v30, 0xffff0000, v30
	v_lshlrev_b32_e32 v57, 16, v31
	v_and_b32_e32 v31, 0xffff0000, v31
	v_add_f32_e32 v40, v40, v51
	v_add_f32_e32 v37, v37, v53
	v_add_f32_e32 v28, v41, v28
	v_add_f32_e32 v38, v38, v54
	v_add_f32_e32 v29, v42, v29
	v_add_f32_e32 v39, v39, v55
	v_add_f32_e32 v30, v43, v30
	v_add_f32_e32 v31, v44, v31
	v_add_f32_e32 v40, v40, v57
	v_fma_f32 v37, v36, v37, -v45
	v_fma_f32 v28, v36, v28, -v46
	v_fma_f32 v38, v36, v38, -v47
	v_fma_f32 v29, v36, v29, -v48
	v_fma_f32 v39, v36, v39, -v49
	v_fma_f32 v30, v36, v30, -v50
	v_fma_f32 v31, v36, v31, -v52
	v_fma_f32 v40, v36, v40, -v51
	v_cvt_pk_bf16_f32 v36, v37, v28
	v_cvt_pk_bf16_f32 v37, v38, v29
	v_cvt_pk_bf16_f32 v38, v39, v30
	v_cvt_pk_bf16_f32 v39, v40, v31
	s_waitcnt vmcnt(0)
	v_mfma_f32_16x16x32_bf16 v[28:31], v[182:185], v[36:39], v[20:23]
	s_nop 2
	s_waitcnt vmcnt(0)
	v_mfma_f32_16x16x32_bf16 v[24:27], v[186:189], v[36:39], v[24:27]
	s_waitcnt vmcnt(0)
	v_mfma_f32_16x16x32_bf16 v[20:23], v[190:193], v[36:39], v[32:35]
	s_nop 2
	s_waitcnt vmcnt(0)
	v_mfma_f32_16x16x32_bf16 v[16:19], v[194:197], v[36:39], v[16:19]
	v_max_i32_e32 v32, 4, v56
	v_min_i32_e32 v33, 0x1ffc, v56
	v_sub_u32_e32 v32, v33, v32
	v_add_u32_e32 v32, 8, v32
	v_cvt_f32_i32_e32 v32, v32
	v_div_scale_f32 v33, s[18:19], v32, v32, 1.0
	v_rcp_f32_e32 v34, v33
	s_nop 0
	v_fma_f32 v35, -v33, v34, 1.0
	v_fmac_f32_e32 v34, v35, v34
	v_div_scale_f32 v35, vcc, 1.0, v32, 1.0
	v_mul_f32_e32 v36, v35, v34
	v_fma_f32 v37, -v33, v36, v35
	v_fmac_f32_e32 v36, v37, v34
	v_fma_f32 v33, -v33, v36, v35
	v_div_fmas_f32 v33, v33, v34, v36
	v_div_fixup_f32 v40, v33, v32, 1.0
	ds_read_b128 v[32:35], v149 offset:2368
	s_waitcnt lgkmcnt(0)
	v_lshlrev_b32_e32 v36, 16, v32
	v_and_b32_e32 v32, 0xffff0000, v32
	v_lshlrev_b32_e32 v37, 16, v33
	v_and_b32_e32 v33, 0xffff0000, v33
	v_lshlrev_b32_e32 v38, 16, v34
	v_and_b32_e32 v34, 0xffff0000, v34
	v_lshlrev_b32_e32 v39, 16, v35
	v_and_b32_e32 v35, 0xffff0000, v35
	v_add_f32_e32 v41, 0, v32
	v_add_f32_e32 v42, 0, v33
	v_add_f32_e32 v43, 0, v34
	v_add_f32_e32 v44, 0, v35
	ds_read_b128 v[32:35], v149 offset:2896
	v_add_f32_e32 v36, 0, v36
	v_add_f32_e32 v37, 0, v37
	v_add_f32_e32 v38, 0, v38
	v_add_f32_e32 v39, 0, v39
	s_waitcnt lgkmcnt(0)
	v_lshlrev_b32_e32 v45, 16, v32
	v_and_b32_e32 v32, 0xffff0000, v32
	v_lshlrev_b32_e32 v46, 16, v33
	v_and_b32_e32 v33, 0xffff0000, v33
	v_lshlrev_b32_e32 v47, 16, v34
	v_and_b32_e32 v34, 0xffff0000, v34
	v_lshlrev_b32_e32 v48, 16, v35
	v_and_b32_e32 v35, 0xffff0000, v35
	v_add_f32_e32 v41, v41, v32
	v_add_f32_e32 v42, v42, v33
	v_add_f32_e32 v43, v43, v34
	v_add_f32_e32 v44, v44, v35
	ds_read_b128 v[32:35], v149 offset:3424
	v_add_f32_e32 v36, v36, v45
	v_add_f32_e32 v37, v37, v46
	v_add_f32_e32 v38, v38, v47
	v_add_f32_e32 v39, v39, v48
	s_waitcnt lgkmcnt(0)
	v_lshlrev_b32_e32 v45, 16, v32
	v_and_b32_e32 v32, 0xffff0000, v32
	v_lshlrev_b32_e32 v46, 16, v33
	v_and_b32_e32 v33, 0xffff0000, v33
	v_lshlrev_b32_e32 v47, 16, v34
	v_and_b32_e32 v34, 0xffff0000, v34
	v_lshlrev_b32_e32 v48, 16, v35
	v_and_b32_e32 v35, 0xffff0000, v35
	v_add_f32_e32 v41, v41, v32
	v_add_f32_e32 v42, v42, v33
	v_add_f32_e32 v43, v43, v34
	v_add_f32_e32 v44, v44, v35
	ds_read_b128 v[32:35], v149 offset:3952
	v_add_f32_e32 v36, v36, v45
	v_add_f32_e32 v37, v37, v46
	v_add_f32_e32 v38, v38, v47
	v_add_f32_e32 v39, v39, v48
	s_waitcnt lgkmcnt(0)
	v_lshlrev_b32_e32 v45, 16, v32
	v_lshlrev_b32_e32 v46, 16, v33
	v_lshlrev_b32_e32 v47, 16, v34
	v_lshlrev_b32_e32 v48, 16, v35
	v_add_f32_e32 v45, v36, v45
	v_add_f32_e32 v46, v37, v46
	v_add_f32_e32 v47, v38, v47
	v_add_f32_e32 v48, v39, v48
	ds_read_b128 v[36:39], v149 offset:4480
	v_and_b32_e32 v32, 0xffff0000, v32
	v_and_b32_e32 v33, 0xffff0000, v33
	v_and_b32_e32 v34, 0xffff0000, v34
	v_and_b32_e32 v35, 0xffff0000, v35
	v_add_f32_e32 v41, v41, v32
	v_add_f32_e32 v42, v42, v33
	v_add_f32_e32 v43, v43, v34
	v_add_f32_e32 v44, v44, v35
	s_waitcnt lgkmcnt(0)
	v_lshlrev_b32_e32 v32, 16, v36
	v_and_b32_e32 v33, 0xffff0000, v36
	v_lshlrev_b32_e32 v34, 16, v37
	v_and_b32_e32 v35, 0xffff0000, v37
	v_lshlrev_b32_e32 v36, 16, v38
	v_and_b32_e32 v37, 0xffff0000, v38
	v_lshlrev_b32_e32 v38, 16, v39
	v_and_b32_e32 v39, 0xffff0000, v39
	v_add_f32_e32 v49, v45, v32
	v_add_f32_e32 v50, v42, v35
	v_add_f32_e32 v51, v43, v37
	v_add_f32_e32 v52, v44, v39
	ds_read_b128 v[42:45], v149 offset:5008
	v_add_f32_e32 v41, v41, v33
	v_add_f32_e32 v46, v46, v34
	v_add_f32_e32 v47, v47, v36
	v_add_f32_e32 v48, v48, v38
	s_waitcnt lgkmcnt(0)
	v_lshlrev_b32_e32 v53, 16, v42
	v_and_b32_e32 v42, 0xffff0000, v42
	v_lshlrev_b32_e32 v54, 16, v43
	v_and_b32_e32 v43, 0xffff0000, v43
	v_lshlrev_b32_e32 v55, 16, v44
	v_and_b32_e32 v44, 0xffff0000, v44
	v_lshlrev_b32_e32 v57, 16, v45
	v_and_b32_e32 v45, 0xffff0000, v45
	v_add_f32_e32 v49, v49, v53
	v_add_f32_e32 v53, v41, v42
	v_add_f32_e32 v50, v50, v43
	v_add_f32_e32 v51, v51, v44
	v_add_f32_e32 v52, v52, v45
	ds_read_b128 v[42:45], v149 offset:5536
	v_add_f32_e32 v46, v46, v54
	v_add_f32_e32 v47, v47, v55
	v_add_f32_e32 v48, v48, v57
	s_waitcnt lgkmcnt(0)
	v_lshlrev_b32_e32 v41, 16, v42
	v_and_b32_e32 v42, 0xffff0000, v42
	v_lshlrev_b32_e32 v54, 16, v43
	v_and_b32_e32 v55, 0xffff0000, v43
	v_lshlrev_b32_e32 v57, 16, v44
	v_and_b32_e32 v58, 0xffff0000, v44
	v_lshlrev_b32_e32 v59, 16, v45
	v_and_b32_e32 v60, 0xffff0000, v45
	v_add_f32_e32 v42, v53, v42
	v_add_f32_e32 v43, v46, v54
	v_add_f32_e32 v44, v50, v55
	v_add_f32_e32 v45, v47, v57
	v_add_f32_e32 v46, v51, v58
	v_add_f32_e32 v47, v48, v59
	v_add_f32_e32 v48, v52, v60
	ds_read_b128 v[50:53], v149 offset:6064
	v_add_f32_e32 v41, v49, v41
	s_waitcnt lgkmcnt(0)
	v_lshlrev_b32_e32 v49, 16, v50
	v_and_b32_e32 v50, 0xffff0000, v50
	v_lshlrev_b32_e32 v54, 16, v51
	v_and_b32_e32 v51, 0xffff0000, v51
	v_lshlrev_b32_e32 v55, 16, v52
	v_and_b32_e32 v52, 0xffff0000, v52
	v_lshlrev_b32_e32 v57, 16, v53
	v_and_b32_e32 v53, 0xffff0000, v53
	v_add_f32_e32 v41, v41, v49
	v_add_f32_e32 v42, v42, v50
	v_add_f32_e32 v43, v43, v54
	v_add_f32_e32 v44, v44, v51
	v_add_f32_e32 v45, v45, v55
	v_add_f32_e32 v46, v46, v52
	v_add_f32_e32 v47, v47, v57
	v_add_f32_e32 v48, v48, v53
	v_fma_f32 v32, v40, v41, -v32
	v_fma_f32 v33, v40, v42, -v33
	v_fma_f32 v34, v40, v43, -v34
	v_fma_f32 v35, v40, v44, -v35
	v_fma_f32 v36, v40, v45, -v36
	v_fma_f32 v37, v40, v46, -v37
	v_fma_f32 v38, v40, v47, -v38
	v_fma_f32 v39, v40, v48, -v39
	v_cvt_pk_bf16_f32 v42, v32, v33
	v_cvt_pk_bf16_f32 v43, v34, v35
	v_cvt_pk_bf16_f32 v44, v36, v37
	v_cvt_pk_bf16_f32 v45, v38, v39
	global_load_dwordx4 v[32:35], v[98:99], off
	global_load_dwordx4 v[36:39], v[100:101], off
	global_load_dwordx4 v[46:49], v[102:103], off
	global_load_dwordx4 v[52:55], v[104:105], off
	s_waitcnt vmcnt(3)
	v_mfma_f32_16x16x32_bf16 v[32:35], v[32:35], v[42:45], 0
	s_waitcnt vmcnt(2)
	v_mfma_f32_16x16x32_bf16 v[36:39], v[36:39], v[42:45], 0
	s_waitcnt vmcnt(1)
	v_mfma_f32_16x16x32_bf16 v[48:51], v[46:49], v[42:45], 0
	s_waitcnt vmcnt(0)
	v_mfma_f32_16x16x32_bf16 v[52:55], v[52:55], v[42:45], 0
	ds_read_b128 v[42:45], v149 offset:2432
	s_waitcnt lgkmcnt(0)
	v_lshlrev_b32_e32 v41, 16, v42
	v_and_b32_e32 v42, 0xffff0000, v42
	v_lshlrev_b32_e32 v46, 16, v43
	v_and_b32_e32 v43, 0xffff0000, v43
	v_lshlrev_b32_e32 v47, 16, v44
	v_and_b32_e32 v44, 0xffff0000, v44
	v_lshlrev_b32_e32 v57, 16, v45
	v_and_b32_e32 v45, 0xffff0000, v45
	v_add_f32_e32 v58, 0, v42
	v_add_f32_e32 v59, 0, v43
	v_add_f32_e32 v60, 0, v44
	v_add_f32_e32 v61, 0, v45
	ds_read_b128 v[42:45], v149 offset:2960
	v_add_f32_e32 v41, 0, v41
	v_add_f32_e32 v46, 0, v46
	v_add_f32_e32 v47, 0, v47
	v_add_f32_e32 v57, 0, v57
	s_waitcnt lgkmcnt(0)
	v_lshlrev_b32_e32 v62, 16, v42
	v_and_b32_e32 v42, 0xffff0000, v42
	v_lshlrev_b32_e32 v63, 16, v43
	v_and_b32_e32 v43, 0xffff0000, v43
	v_lshlrev_b32_e32 v64, 16, v44
	v_and_b32_e32 v44, 0xffff0000, v44
	v_lshlrev_b32_e32 v65, 16, v45
	v_and_b32_e32 v45, 0xffff0000, v45
	v_add_f32_e32 v58, v58, v42
	v_add_f32_e32 v59, v59, v43
	v_add_f32_e32 v60, v60, v44
	v_add_f32_e32 v61, v61, v45
	ds_read_b128 v[42:45], v149 offset:3488
	v_add_f32_e32 v41, v41, v62
	v_add_f32_e32 v46, v46, v63
	v_add_f32_e32 v47, v47, v64
	v_add_f32_e32 v57, v57, v65
	s_waitcnt lgkmcnt(0)
	v_lshlrev_b32_e32 v62, 16, v42
	v_and_b32_e32 v42, 0xffff0000, v42
	v_lshlrev_b32_e32 v63, 16, v43
	v_and_b32_e32 v43, 0xffff0000, v43
	v_lshlrev_b32_e32 v64, 16, v44
	v_and_b32_e32 v44, 0xffff0000, v44
	v_lshlrev_b32_e32 v65, 16, v45
	v_and_b32_e32 v45, 0xffff0000, v45
	v_add_f32_e32 v58, v58, v42
	v_add_f32_e32 v59, v59, v43
	v_add_f32_e32 v60, v60, v44
	v_add_f32_e32 v61, v61, v45
	ds_read_b128 v[42:45], v149 offset:4016
	v_add_f32_e32 v41, v41, v62
	v_add_f32_e32 v46, v46, v63
	v_add_f32_e32 v47, v47, v64
	v_add_f32_e32 v57, v57, v65
	s_waitcnt lgkmcnt(0)
	v_lshlrev_b32_e32 v62, 16, v42
	v_and_b32_e32 v42, 0xffff0000, v42
	v_lshlrev_b32_e32 v63, 16, v43
	v_and_b32_e32 v43, 0xffff0000, v43
	v_lshlrev_b32_e32 v64, 16, v44
	v_and_b32_e32 v44, 0xffff0000, v44
	v_lshlrev_b32_e32 v65, 16, v45
	v_and_b32_e32 v45, 0xffff0000, v45
	v_add_f32_e32 v66, v58, v42
	v_add_f32_e32 v67, v59, v43
	v_add_f32_e32 v68, v60, v44
	v_add_f32_e32 v69, v61, v45
	ds_read_b128 v[58:61], v149 offset:4544
	v_add_f32_e32 v62, v41, v62
	v_add_f32_e32 v63, v46, v63
	v_add_f32_e32 v64, v47, v64
	v_add_f32_e32 v65, v57, v65
	s_waitcnt lgkmcnt(0)
	v_lshlrev_b32_e32 v41, 16, v58
	v_and_b32_e32 v42, 0xffff0000, v58
	v_lshlrev_b32_e32 v43, 16, v59
	v_and_b32_e32 v44, 0xffff0000, v59
	v_lshlrev_b32_e32 v45, 16, v60
	v_and_b32_e32 v46, 0xffff0000, v60
	v_lshlrev_b32_e32 v47, 16, v61
	v_and_b32_e32 v57, 0xffff0000, v61
	ds_read_b128 v[58:61], v149 offset:5072
	v_add_f32_e32 v66, v66, v42
	v_add_f32_e32 v67, v67, v44
	v_add_f32_e32 v68, v68, v46
	v_add_f32_e32 v69, v69, v57
	s_waitcnt lgkmcnt(0)
	v_lshlrev_b32_e32 v70, 16, v58
	v_and_b32_e32 v58, 0xffff0000, v58
	v_lshlrev_b32_e32 v71, 16, v59
	v_and_b32_e32 v59, 0xffff0000, v59
	v_lshlrev_b32_e32 v131, 16, v60
	v_and_b32_e32 v60, 0xffff0000, v60
	v_lshlrev_b32_e32 v133, 16, v61
	v_and_b32_e32 v61, 0xffff0000, v61
	v_add_f32_e32 v66, v66, v58
	v_add_f32_e32 v67, v67, v59
	v_add_f32_e32 v68, v68, v60
	v_add_f32_e32 v69, v69, v61
	ds_read_b128 v[58:61], v149 offset:5600
	v_add_f32_e32 v62, v62, v41
	v_add_f32_e32 v63, v63, v43
	v_add_f32_e32 v64, v64, v45
	v_add_f32_e32 v65, v65, v47
	v_add_f32_e32 v62, v62, v70
	v_add_f32_e32 v63, v63, v71
	v_add_f32_e32 v64, v64, v131
	v_add_f32_e32 v65, v65, v133
	s_waitcnt lgkmcnt(0)
	v_lshlrev_b32_e32 v70, 16, v58
	v_and_b32_e32 v71, 0xffff0000, v58
	v_lshlrev_b32_e32 v131, 16, v59
	v_and_b32_e32 v133, 0xffff0000, v59
	v_lshlrev_b32_e32 v151, 16, v60
	v_and_b32_e32 v152, 0xffff0000, v60
	v_lshlrev_b32_e32 v153, 16, v61
	v_and_b32_e32 v154, 0xffff0000, v61
	v_add_f32_e32 v58, v62, v70
	v_add_f32_e32 v59, v66, v71
	v_add_f32_e32 v60, v63, v131
	v_add_f32_e32 v61, v67, v133
	v_add_f32_e32 v62, v64, v151
	v_add_f32_e32 v63, v68, v152
	v_add_f32_e32 v64, v65, v153
	v_add_f32_e32 v65, v69, v154
	ds_read_b128 v[66:69], v149 offset:6128
	s_waitcnt lgkmcnt(0)
	v_lshlrev_b32_e32 v70, 16, v66
	v_and_b32_e32 v66, 0xffff0000, v66
	v_lshlrev_b32_e32 v71, 16, v67
	v_and_b32_e32 v67, 0xffff0000, v67
	v_lshlrev_b32_e32 v131, 16, v68
	v_and_b32_e32 v68, 0xffff0000, v68
	v_lshlrev_b32_e32 v133, 16, v69
	v_and_b32_e32 v69, 0xffff0000, v69
	v_add_f32_e32 v58, v58, v70
	v_add_f32_e32 v59, v59, v66
	v_add_f32_e32 v60, v60, v71
	v_add_f32_e32 v61, v61, v67
	v_add_f32_e32 v62, v62, v131
	v_add_f32_e32 v63, v63, v68
	v_add_f32_e32 v64, v64, v133
	v_add_f32_e32 v65, v65, v69
	v_fma_f32 v41, v40, v58, -v41
	v_fma_f32 v42, v40, v59, -v42
	v_fma_f32 v43, v40, v60, -v43
	v_fma_f32 v44, v40, v61, -v44
	v_fma_f32 v45, v40, v62, -v45
	v_fma_f32 v46, v40, v63, -v46
	v_fma_f32 v47, v40, v64, -v47
	v_fma_f32 v40, v40, v65, -v57
	v_cvt_pk_bf16_f32 v58, v41, v42
	v_cvt_pk_bf16_f32 v59, v43, v44
	v_cvt_pk_bf16_f32 v60, v45, v46
	v_cvt_pk_bf16_f32 v61, v47, v40
	s_waitcnt vmcnt(0)
	v_mfma_f32_16x16x32_bf16 v[44:47], v[198:201], v[58:61], v[32:35]
	s_nop 2
	s_waitcnt vmcnt(0)
	v_mfma_f32_16x16x32_bf16 v[40:43], v[202:205], v[58:61], v[36:39]
	s_waitcnt vmcnt(0)
	v_mfma_f32_16x16x32_bf16 v[36:39], v[214:217], v[58:61], v[48:51]
	s_nop 1
	v_max_i32_e32 v48, 8, v56
	v_min_i32_e32 v49, 0x1ff8, v56
	v_sub_u32_e32 v48, v49, v48
	v_add_u32_e32 v48, 16, v48
	v_cvt_f32_i32_e32 v48, v48
	s_waitcnt vmcnt(0)
	v_mfma_f32_16x16x32_bf16 v[32:35], v[218:221], v[58:61], v[52:55]
	v_div_scale_f32 v49, s[18:19], v48, v48, 1.0
	v_rcp_f32_e32 v50, v49
	s_mov_b64 s[18:19], 0x1a000200
	v_fma_f32 v51, -v49, v50, 1.0
	v_fmac_f32_e32 v50, v51, v50
	v_div_scale_f32 v51, vcc, 1.0, v48, 1.0
	v_mul_f32_e32 v52, v51, v50
	v_fma_f32 v53, -v49, v52, v51
	v_fmac_f32_e32 v52, v53, v50
	v_fma_f32 v49, -v49, v52, v51
	v_div_fmas_f32 v49, v49, v50, v52
	v_div_fixup_f32 v56, v49, v48, 1.0
	ds_read_b128 v[48:51], v149 offset:384
	s_waitcnt lgkmcnt(0)
	v_lshlrev_b32_e32 v52, 16, v48
	v_and_b32_e32 v48, 0xffff0000, v48
	v_lshlrev_b32_e32 v53, 16, v49
	v_and_b32_e32 v49, 0xffff0000, v49
	v_lshlrev_b32_e32 v54, 16, v50
	v_and_b32_e32 v50, 0xffff0000, v50
	v_lshlrev_b32_e32 v55, 16, v51
	v_and_b32_e32 v51, 0xffff0000, v51
	v_add_f32_e32 v57, 0, v48
	v_add_f32_e32 v58, 0, v49
	v_add_f32_e32 v59, 0, v50
	v_add_f32_e32 v60, 0, v51
	ds_read_b128 v[48:51], v149 offset:912
	v_add_f32_e32 v52, 0, v52
	v_add_f32_e32 v53, 0, v53
	v_add_f32_e32 v54, 0, v54
	v_add_f32_e32 v55, 0, v55
	s_waitcnt lgkmcnt(0)
	v_lshlrev_b32_e32 v61, 16, v48
	v_and_b32_e32 v48, 0xffff0000, v48
	v_lshlrev_b32_e32 v62, 16, v49
	v_and_b32_e32 v49, 0xffff0000, v49
	v_lshlrev_b32_e32 v63, 16, v50
	v_and_b32_e32 v50, 0xffff0000, v50
	v_lshlrev_b32_e32 v64, 16, v51
	v_and_b32_e32 v51, 0xffff0000, v51
	v_add_f32_e32 v57, v57, v48
	v_add_f32_e32 v58, v58, v49
	v_add_f32_e32 v59, v59, v50
	v_add_f32_e32 v60, v60, v51
	ds_read_b128 v[48:51], v149 offset:1440
	v_add_f32_e32 v52, v52, v61
	v_add_f32_e32 v53, v53, v62
	v_add_f32_e32 v54, v54, v63
	v_add_f32_e32 v55, v55, v64
	s_waitcnt lgkmcnt(0)
	v_lshlrev_b32_e32 v61, 16, v48
	v_and_b32_e32 v48, 0xffff0000, v48
	v_lshlrev_b32_e32 v62, 16, v49
	v_and_b32_e32 v49, 0xffff0000, v49
	v_lshlrev_b32_e32 v63, 16, v50
	v_and_b32_e32 v50, 0xffff0000, v50
	v_lshlrev_b32_e32 v64, 16, v51
	v_and_b32_e32 v51, 0xffff0000, v51
	v_add_f32_e32 v57, v57, v48
	v_add_f32_e32 v58, v58, v49
	v_add_f32_e32 v59, v59, v50
	v_add_f32_e32 v60, v60, v51
	ds_read_b128 v[48:51], v149 offset:1968
	v_add_f32_e32 v52, v52, v61
	v_add_f32_e32 v53, v53, v62
	v_add_f32_e32 v54, v54, v63
	v_add_f32_e32 v55, v55, v64
	s_waitcnt lgkmcnt(0)
	v_lshlrev_b32_e32 v61, 16, v48
	v_and_b32_e32 v48, 0xffff0000, v48
	v_lshlrev_b32_e32 v62, 16, v49
	v_and_b32_e32 v49, 0xffff0000, v49
	v_lshlrev_b32_e32 v63, 16, v50
	v_and_b32_e32 v50, 0xffff0000, v50
	v_lshlrev_b32_e32 v64, 16, v51
	v_and_b32_e32 v51, 0xffff0000, v51
	v_add_f32_e32 v57, v57, v48
	v_add_f32_e32 v58, v58, v49
	v_add_f32_e32 v59, v59, v50
	v_add_f32_e32 v60, v60, v51
	ds_read_b128 v[48:51], v149 offset:2496
	v_add_f32_e32 v52, v52, v61
	v_add_f32_e32 v53, v53, v62
	v_add_f32_e32 v54, v54, v63
	v_add_f32_e32 v55, v55, v64
	s_waitcnt lgkmcnt(0)
	v_lshlrev_b32_e32 v61, 16, v48
	v_and_b32_e32 v48, 0xffff0000, v48
	v_lshlrev_b32_e32 v62, 16, v49
	v_and_b32_e32 v49, 0xffff0000, v49
	v_lshlrev_b32_e32 v63, 16, v50
	v_and_b32_e32 v50, 0xffff0000, v50
	v_lshlrev_b32_e32 v64, 16, v51
	v_and_b32_e32 v51, 0xffff0000, v51
	v_add_f32_e32 v57, v57, v48
	v_add_f32_e32 v58, v58, v49
	v_add_f32_e32 v59, v59, v50
	v_add_f32_e32 v60, v60, v51
	ds_read_b128 v[48:51], v149 offset:3024
	v_add_f32_e32 v52, v52, v61
	v_add_f32_e32 v53, v53, v62
	v_add_f32_e32 v54, v54, v63
	v_add_f32_e32 v55, v55, v64
	s_waitcnt lgkmcnt(0)
	v_lshlrev_b32_e32 v61, 16, v48
	v_and_b32_e32 v48, 0xffff0000, v48
	v_lshlrev_b32_e32 v62, 16, v49
	v_and_b32_e32 v49, 0xffff0000, v49
	v_lshlrev_b32_e32 v63, 16, v50
	v_and_b32_e32 v50, 0xffff0000, v50
	v_lshlrev_b32_e32 v64, 16, v51
	v_and_b32_e32 v51, 0xffff0000, v51
	v_add_f32_e32 v57, v57, v48
	v_add_f32_e32 v58, v58, v49
	v_add_f32_e32 v59, v59, v50
	v_add_f32_e32 v60, v60, v51
	ds_read_b128 v[48:51], v149 offset:3552
	v_add_f32_e32 v52, v52, v61
	v_add_f32_e32 v53, v53, v62
	v_add_f32_e32 v54, v54, v63
	v_add_f32_e32 v55, v55, v64
	s_waitcnt lgkmcnt(0)
	v_lshlrev_b32_e32 v61, 16, v48
	v_and_b32_e32 v48, 0xffff0000, v48
	v_lshlrev_b32_e32 v62, 16, v49
	v_and_b32_e32 v49, 0xffff0000, v49
	v_lshlrev_b32_e32 v63, 16, v50
	v_and_b32_e32 v50, 0xffff0000, v50
	v_lshlrev_b32_e32 v64, 16, v51
	v_and_b32_e32 v51, 0xffff0000, v51
	v_add_f32_e32 v57, v57, v48
	v_add_f32_e32 v58, v58, v49
	v_add_f32_e32 v59, v59, v50
	v_add_f32_e32 v60, v60, v51
	ds_read_b128 v[48:51], v149 offset:4080
	v_add_f32_e32 v52, v52, v61
	v_add_f32_e32 v53, v53, v62
	v_add_f32_e32 v54, v54, v63
	v_add_f32_e32 v55, v55, v64
	s_waitcnt lgkmcnt(0)
	v_lshlrev_b32_e32 v61, 16, v48
	v_lshlrev_b32_e32 v62, 16, v49
	v_lshlrev_b32_e32 v63, 16, v50
	v_lshlrev_b32_e32 v64, 16, v51
	v_add_f32_e32 v61, v52, v61
	v_add_f32_e32 v62, v53, v62
	v_add_f32_e32 v63, v54, v63
	v_add_f32_e32 v64, v55, v64
	ds_read_b128 v[52:55], v149 offset:4608
	v_and_b32_e32 v48, 0xffff0000, v48
	v_and_b32_e32 v49, 0xffff0000, v49
	v_and_b32_e32 v50, 0xffff0000, v50
	v_and_b32_e32 v51, 0xffff0000, v51
	v_add_f32_e32 v57, v57, v48
	v_add_f32_e32 v58, v58, v49
	v_add_f32_e32 v59, v59, v50
	v_add_f32_e32 v60, v60, v51
	s_waitcnt lgkmcnt(0)
	v_lshlrev_b32_e32 v48, 16, v52
	v_and_b32_e32 v49, 0xffff0000, v52
	v_lshlrev_b32_e32 v50, 16, v53
	v_and_b32_e32 v51, 0xffff0000, v53
	v_lshlrev_b32_e32 v52, 16, v54
	v_and_b32_e32 v53, 0xffff0000, v54
	v_lshlrev_b32_e32 v54, 16, v55
	v_and_b32_e32 v55, 0xffff0000, v55
	v_add_f32_e32 v65, v61, v48
	v_add_f32_e32 v66, v58, v51
	v_add_f32_e32 v67, v59, v53
	v_add_f32_e32 v68, v60, v55
	ds_read_b128 v[58:61], v149 offset:5136
	v_add_f32_e32 v57, v57, v49
	v_add_f32_e32 v62, v62, v50
	v_add_f32_e32 v63, v63, v52
	v_add_f32_e32 v64, v64, v54
	s_waitcnt lgkmcnt(0)
	v_lshlrev_b32_e32 v69, 16, v58
	v_and_b32_e32 v58, 0xffff0000, v58
	v_lshlrev_b32_e32 v70, 16, v59
	v_and_b32_e32 v59, 0xffff0000, v59
	v_lshlrev_b32_e32 v71, 16, v60
	v_and_b32_e32 v60, 0xffff0000, v60
	v_lshlrev_b32_e32 v131, 16, v61
	v_and_b32_e32 v61, 0xffff0000, v61
	v_add_f32_e32 v57, v57, v58
	v_add_f32_e32 v66, v66, v59
	v_add_f32_e32 v67, v67, v60
	v_add_f32_e32 v68, v68, v61
	ds_read_b128 v[58:61], v149 offset:5664
	v_add_f32_e32 v65, v65, v69
	v_add_f32_e32 v62, v62, v70
	v_add_f32_e32 v63, v63, v71
	v_add_f32_e32 v64, v64, v131
	s_waitcnt lgkmcnt(0)
	v_lshlrev_b32_e32 v69, 16, v58
	v_and_b32_e32 v58, 0xffff0000, v58
	v_lshlrev_b32_e32 v70, 16, v59
	v_and_b32_e32 v59, 0xffff0000, v59
	v_lshlrev_b32_e32 v71, 16, v60
	v_and_b32_e32 v60, 0xffff0000, v60
	v_lshlrev_b32_e32 v131, 16, v61
	v_and_b32_e32 v61, 0xffff0000, v61
	v_add_f32_e32 v57, v57, v58
	v_add_f32_e32 v66, v66, v59
	v_add_f32_e32 v67, v67, v60
	v_add_f32_e32 v68, v68, v61
	ds_read_b128 v[58:61], v149 offset:6192
	v_add_f32_e32 v65, v65, v69
	v_add_f32_e32 v62, v62, v70
	v_add_f32_e32 v63, v63, v71
	v_add_f32_e32 v64, v64, v131
	s_waitcnt lgkmcnt(0)
	v_lshlrev_b32_e32 v69, 16, v58
	v_and_b32_e32 v58, 0xffff0000, v58
	v_lshlrev_b32_e32 v70, 16, v59
	v_and_b32_e32 v59, 0xffff0000, v59
	v_lshlrev_b32_e32 v71, 16, v60
	v_and_b32_e32 v60, 0xffff0000, v60
	v_lshlrev_b32_e32 v131, 16, v61
	v_and_b32_e32 v61, 0xffff0000, v61
	v_add_f32_e32 v57, v57, v58
	v_add_f32_e32 v66, v66, v59
	v_add_f32_e32 v67, v67, v60
	v_add_f32_e32 v68, v68, v61
	ds_read_b128 v[58:61], v149 offset:6720
	v_add_f32_e32 v65, v65, v69
	v_add_f32_e32 v62, v62, v70
	v_add_f32_e32 v63, v63, v71
	v_add_f32_e32 v64, v64, v131
	s_waitcnt lgkmcnt(0)
	v_lshlrev_b32_e32 v69, 16, v58
	v_and_b32_e32 v58, 0xffff0000, v58
	v_lshlrev_b32_e32 v70, 16, v59
	v_and_b32_e32 v59, 0xffff0000, v59
	v_lshlrev_b32_e32 v71, 16, v60
	v_and_b32_e32 v60, 0xffff0000, v60
	v_lshlrev_b32_e32 v131, 16, v61
	v_and_b32_e32 v61, 0xffff0000, v61
	v_add_f32_e32 v57, v57, v58
	v_add_f32_e32 v66, v66, v59
	v_add_f32_e32 v67, v67, v60
	v_add_f32_e32 v68, v68, v61
	ds_read_b128 v[58:61], v149 offset:7248
	v_add_f32_e32 v65, v65, v69
	v_add_f32_e32 v62, v62, v70
	v_add_f32_e32 v63, v63, v71
	v_add_f32_e32 v64, v64, v131
	s_waitcnt lgkmcnt(0)
	v_lshlrev_b32_e32 v69, 16, v58
	v_and_b32_e32 v58, 0xffff0000, v58
	v_lshlrev_b32_e32 v70, 16, v59
	v_and_b32_e32 v59, 0xffff0000, v59
	v_lshlrev_b32_e32 v71, 16, v60
	v_and_b32_e32 v60, 0xffff0000, v60
	v_lshlrev_b32_e32 v131, 16, v61
	v_and_b32_e32 v61, 0xffff0000, v61
	v_add_f32_e32 v65, v65, v69
	v_add_f32_e32 v69, v57, v58
	v_add_f32_e32 v66, v66, v59
	v_add_f32_e32 v67, v67, v60
	v_add_f32_e32 v68, v68, v61
	ds_read_b128 v[58:61], v149 offset:7776
	v_add_f32_e32 v63, v63, v71
	v_add_f32_e32 v64, v64, v131
	v_add_f32_e32 v62, v62, v70
	s_waitcnt lgkmcnt(0)
	v_lshlrev_b32_e32 v131, 16, v60
	v_lshlrev_b32_e32 v151, 16, v61
	v_and_b32_e32 v152, 0xffff0000, v61
	v_add_f32_e32 v61, v63, v131
	v_add_f32_e32 v63, v64, v151
	v_add_f32_e32 v64, v68, v152
	ds_read_b128 v[152:155], v149 offset:8304
	v_lshlrev_b32_e32 v57, 16, v58
	v_and_b32_e32 v58, 0xffff0000, v58
	v_lshlrev_b32_e32 v70, 16, v59
	v_and_b32_e32 v71, 0xffff0000, v59
	v_and_b32_e32 v133, 0xffff0000, v60
	v_add_f32_e32 v57, v65, v57
	v_add_f32_e32 v58, v69, v58
	v_add_f32_e32 v59, v62, v70
	v_add_f32_e32 v60, v66, v71
	v_add_f32_e32 v62, v67, v133
	s_waitcnt lgkmcnt(0)
	v_lshlrev_b32_e32 v65, 16, v152
	v_and_b32_e32 v66, 0xffff0000, v152
	v_lshlrev_b32_e32 v67, 16, v153
	v_and_b32_e32 v68, 0xffff0000, v153
	v_lshlrev_b32_e32 v69, 16, v154
	v_and_b32_e32 v70, 0xffff0000, v154
	v_lshlrev_b32_e32 v71, 16, v155
	v_and_b32_e32 v131, 0xffff0000, v155
	v_add_f32_e32 v57, v57, v65
	v_add_f32_e32 v58, v58, v66
	v_add_f32_e32 v59, v59, v67
	v_add_f32_e32 v60, v60, v68
	v_add_f32_e32 v61, v61, v69
	v_add_f32_e32 v62, v62, v70
	v_add_f32_e32 v63, v63, v71
	v_add_f32_e32 v64, v64, v131
	v_fma_f32 v48, v56, v57, -v48
	v_fma_f32 v49, v56, v58, -v49
	v_fma_f32 v50, v56, v59, -v50
	v_fma_f32 v51, v56, v60, -v51
	v_fma_f32 v52, v56, v61, -v52
	v_fma_f32 v53, v56, v62, -v53
	v_fma_f32 v54, v56, v63, -v54
	v_fma_f32 v55, v56, v64, -v55
	v_cvt_pk_bf16_f32 v58, v48, v49
	v_cvt_pk_bf16_f32 v59, v50, v51
	v_cvt_pk_bf16_f32 v60, v52, v53
	v_cvt_pk_bf16_f32 v61, v54, v55
	global_load_dwordx4 v[48:51], v[114:115], off
	global_load_dwordx4 v[52:55], v[116:117], off
	global_load_dwordx4 v[62:65], v[118:119], off
	global_load_dwordx4 v[68:71], v[120:121], off
	s_waitcnt vmcnt(3)
	v_mfma_f32_16x16x32_bf16 v[48:51], v[48:51], v[58:61], 0
	s_waitcnt vmcnt(2)
	v_mfma_f32_16x16x32_bf16 v[52:55], v[52:55], v[58:61], 0
	s_waitcnt vmcnt(1)
	v_mfma_f32_16x16x32_bf16 v[64:67], v[62:65], v[58:61], 0
	s_waitcnt vmcnt(0)
	v_mfma_f32_16x16x32_bf16 v[68:71], v[68:71], v[58:61], 0
	ds_read_b128 v[58:61], v149 offset:448
	s_waitcnt lgkmcnt(0)
	v_lshlrev_b32_e32 v57, 16, v58
	v_and_b32_e32 v58, 0xffff0000, v58
	v_lshlrev_b32_e32 v62, 16, v59
	v_and_b32_e32 v59, 0xffff0000, v59
	v_lshlrev_b32_e32 v63, 16, v60
	v_and_b32_e32 v60, 0xffff0000, v60
	v_lshlrev_b32_e32 v131, 16, v61
	v_and_b32_e32 v61, 0xffff0000, v61
	v_add_f32_e32 v133, 0, v58
	v_add_f32_e32 v151, 0, v59
	v_add_f32_e32 v152, 0, v60
	v_add_f32_e32 v153, 0, v61
	ds_read_b128 v[58:61], v149 offset:976
	v_add_f32_e32 v57, 0, v57
	v_add_f32_e32 v62, 0, v62
	v_add_f32_e32 v63, 0, v63
	v_add_f32_e32 v131, 0, v131
	s_waitcnt lgkmcnt(0)
	v_lshlrev_b32_e32 v154, 16, v58
	v_and_b32_e32 v58, 0xffff0000, v58
	v_lshlrev_b32_e32 v155, 16, v59
	v_and_b32_e32 v59, 0xffff0000, v59
	v_lshlrev_b32_e32 v156, 16, v60
	v_and_b32_e32 v60, 0xffff0000, v60
	v_lshlrev_b32_e32 v157, 16, v61
	v_and_b32_e32 v61, 0xffff0000, v61
	v_add_f32_e32 v133, v133, v58
	v_add_f32_e32 v151, v151, v59
	v_add_f32_e32 v152, v152, v60
	v_add_f32_e32 v153, v153, v61
	ds_read_b128 v[58:61], v149 offset:1504
	v_add_f32_e32 v57, v57, v154
	v_add_f32_e32 v62, v62, v155
	v_add_f32_e32 v63, v63, v156
	v_add_f32_e32 v131, v131, v157
	s_waitcnt lgkmcnt(0)
	v_lshlrev_b32_e32 v154, 16, v58
	v_and_b32_e32 v58, 0xffff0000, v58
	v_lshlrev_b32_e32 v155, 16, v59
	v_and_b32_e32 v59, 0xffff0000, v59
	v_lshlrev_b32_e32 v156, 16, v60
	v_and_b32_e32 v60, 0xffff0000, v60
	v_lshlrev_b32_e32 v157, 16, v61
	v_and_b32_e32 v61, 0xffff0000, v61
	v_add_f32_e32 v133, v133, v58
	v_add_f32_e32 v151, v151, v59
	v_add_f32_e32 v152, v152, v60
	v_add_f32_e32 v153, v153, v61
	ds_read_b128 v[58:61], v149 offset:2032
	v_add_f32_e32 v57, v57, v154
	v_add_f32_e32 v62, v62, v155
	v_add_f32_e32 v63, v63, v156
	v_add_f32_e32 v131, v131, v157
	s_waitcnt lgkmcnt(0)
	v_lshlrev_b32_e32 v154, 16, v58
	v_and_b32_e32 v58, 0xffff0000, v58
	v_lshlrev_b32_e32 v155, 16, v59
	v_and_b32_e32 v59, 0xffff0000, v59
	v_lshlrev_b32_e32 v156, 16, v60
	v_and_b32_e32 v60, 0xffff0000, v60
	v_lshlrev_b32_e32 v157, 16, v61
	v_and_b32_e32 v61, 0xffff0000, v61
	v_add_f32_e32 v133, v133, v58
	v_add_f32_e32 v151, v151, v59
	v_add_f32_e32 v152, v152, v60
	v_add_f32_e32 v153, v153, v61
	ds_read_b128 v[58:61], v149 offset:2560
	v_add_f32_e32 v57, v57, v154
	v_add_f32_e32 v62, v62, v155
	v_add_f32_e32 v63, v63, v156
	v_add_f32_e32 v131, v131, v157
	s_waitcnt lgkmcnt(0)
	v_lshlrev_b32_e32 v154, 16, v58
	v_and_b32_e32 v58, 0xffff0000, v58
	v_lshlrev_b32_e32 v155, 16, v59
	v_and_b32_e32 v59, 0xffff0000, v59
	v_lshlrev_b32_e32 v156, 16, v60
	v_and_b32_e32 v60, 0xffff0000, v60
	v_lshlrev_b32_e32 v157, 16, v61
	v_and_b32_e32 v61, 0xffff0000, v61
	v_add_f32_e32 v133, v133, v58
	v_add_f32_e32 v151, v151, v59
	v_add_f32_e32 v152, v152, v60
	v_add_f32_e32 v153, v153, v61
	ds_read_b128 v[58:61], v149 offset:3088
	v_add_f32_e32 v57, v57, v154
	v_add_f32_e32 v62, v62, v155
	v_add_f32_e32 v63, v63, v156
	v_add_f32_e32 v131, v131, v157
	s_waitcnt lgkmcnt(0)
	v_lshlrev_b32_e32 v154, 16, v58
	v_and_b32_e32 v58, 0xffff0000, v58
	v_lshlrev_b32_e32 v155, 16, v59
	v_and_b32_e32 v59, 0xffff0000, v59
	v_lshlrev_b32_e32 v156, 16, v60
	v_and_b32_e32 v60, 0xffff0000, v60
	v_lshlrev_b32_e32 v157, 16, v61
	v_and_b32_e32 v61, 0xffff0000, v61
	v_add_f32_e32 v133, v133, v58
	v_add_f32_e32 v151, v151, v59
	v_add_f32_e32 v152, v152, v60
	v_add_f32_e32 v153, v153, v61
	ds_read_b128 v[58:61], v149 offset:3616
	v_add_f32_e32 v57, v57, v154
	v_add_f32_e32 v62, v62, v155
	v_add_f32_e32 v63, v63, v156
	v_add_f32_e32 v131, v131, v157
	s_waitcnt lgkmcnt(0)
	v_lshlrev_b32_e32 v154, 16, v58
	v_and_b32_e32 v58, 0xffff0000, v58
	v_lshlrev_b32_e32 v155, 16, v59
	v_and_b32_e32 v59, 0xffff0000, v59
	v_lshlrev_b32_e32 v156, 16, v60
	v_and_b32_e32 v60, 0xffff0000, v60
	v_lshlrev_b32_e32 v157, 16, v61
	v_and_b32_e32 v61, 0xffff0000, v61
	v_add_f32_e32 v133, v133, v58
	v_add_f32_e32 v151, v151, v59
	v_add_f32_e32 v152, v152, v60
	v_add_f32_e32 v153, v153, v61
	ds_read_b128 v[58:61], v149 offset:4144
	v_add_f32_e32 v57, v57, v154
	v_add_f32_e32 v62, v62, v155
	v_add_f32_e32 v63, v63, v156
	v_add_f32_e32 v131, v131, v157
	s_waitcnt lgkmcnt(0)
	v_lshlrev_b32_e32 v154, 16, v58
	v_lshlrev_b32_e32 v155, 16, v59
	v_lshlrev_b32_e32 v156, 16, v60
	v_and_b32_e32 v60, 0xffff0000, v60
	v_lshlrev_b32_e32 v157, 16, v61
	v_and_b32_e32 v61, 0xffff0000, v61
	v_add_f32_e32 v158, v57, v154
	v_add_f32_e32 v159, v62, v155
	v_add_f32_e32 v160, v152, v60
	v_add_f32_e32 v161, v153, v61
	ds_read_b128 v[152:155], v149 offset:4672
	v_and_b32_e32 v58, 0xffff0000, v58
	v_and_b32_e32 v59, 0xffff0000, v59
	v_add_f32_e32 v133, v133, v58
	v_add_f32_e32 v151, v151, v59
	v_add_f32_e32 v156, v63, v156
	v_add_f32_e32 v157, v131, v157
	s_waitcnt lgkmcnt(0)
	v_lshlrev_b32_e32 v57, 16, v152
	v_and_b32_e32 v58, 0xffff0000, v152
	v_lshlrev_b32_e32 v59, 16, v153
	v_and_b32_e32 v60, 0xffff0000, v153
	v_lshlrev_b32_e32 v61, 16, v154
	v_and_b32_e32 v62, 0xffff0000, v154
	v_lshlrev_b32_e32 v63, 16, v155
	v_and_b32_e32 v131, 0xffff0000, v155
	ds_read_b128 v[152:155], v149 offset:5200
	v_add_f32_e32 v133, v133, v58
	v_add_f32_e32 v151, v151, v60
	v_add_f32_e32 v160, v160, v62
	v_add_f32_e32 v161, v161, v131
	s_waitcnt lgkmcnt(0)
	v_lshlrev_b32_e32 v162, 16, v152
	v_and_b32_e32 v152, 0xffff0000, v152
	v_lshlrev_b32_e32 v163, 16, v153
	v_and_b32_e32 v153, 0xffff0000, v153
	v_lshlrev_b32_e32 v164, 16, v154
	v_and_b32_e32 v154, 0xffff0000, v154
	v_lshlrev_b32_e32 v165, 16, v155
	v_and_b32_e32 v155, 0xffff0000, v155
	v_add_f32_e32 v133, v133, v152
	v_add_f32_e32 v151, v151, v153
	v_add_f32_e32 v160, v160, v154
	v_add_f32_e32 v161, v161, v155
	ds_read_b128 v[152:155], v149 offset:5728
	v_add_f32_e32 v158, v158, v57
	v_add_f32_e32 v159, v159, v59
	v_add_f32_e32 v156, v156, v61
	v_add_f32_e32 v157, v157, v63
	v_add_f32_e32 v158, v158, v162
	v_add_f32_e32 v159, v159, v163
	v_add_f32_e32 v156, v156, v164
	v_add_f32_e32 v157, v157, v165
	s_waitcnt lgkmcnt(0)
	v_lshlrev_b32_e32 v162, 16, v152
	v_and_b32_e32 v152, 0xffff0000, v152
	v_lshlrev_b32_e32 v163, 16, v153
	v_and_b32_e32 v153, 0xffff0000, v153
	v_lshlrev_b32_e32 v164, 16, v154
	v_and_b32_e32 v154, 0xffff0000, v154
	v_lshlrev_b32_e32 v165, 16, v155
	v_and_b32_e32 v155, 0xffff0000, v155
	v_add_f32_e32 v133, v133, v152
	v_add_f32_e32 v151, v151, v153
	v_add_f32_e32 v160, v160, v154
	v_add_f32_e32 v161, v161, v155
	ds_read_b128 v[152:155], v149 offset:6256
	v_add_f32_e32 v158, v158, v162
	v_add_f32_e32 v159, v159, v163
	v_add_f32_e32 v156, v156, v164
	v_add_f32_e32 v157, v157, v165
	s_waitcnt lgkmcnt(0)
	v_lshlrev_b32_e32 v162, 16, v152
	v_and_b32_e32 v152, 0xffff0000, v152
	v_lshlrev_b32_e32 v163, 16, v153
	v_and_b32_e32 v153, 0xffff0000, v153
	v_lshlrev_b32_e32 v164, 16, v154
	v_and_b32_e32 v154, 0xffff0000, v154
	v_lshlrev_b32_e32 v165, 16, v155
	v_and_b32_e32 v155, 0xffff0000, v155
	v_add_f32_e32 v133, v133, v152
	v_add_f32_e32 v151, v151, v153
	v_add_f32_e32 v160, v160, v154
	v_add_f32_e32 v161, v161, v155
	ds_read_b128 v[152:155], v149 offset:6784
	v_add_f32_e32 v158, v158, v162
	v_add_f32_e32 v159, v159, v163
	v_add_f32_e32 v156, v156, v164
	v_add_f32_e32 v157, v157, v165
	s_waitcnt lgkmcnt(0)
	v_lshlrev_b32_e32 v162, 16, v152
	v_and_b32_e32 v152, 0xffff0000, v152
	v_lshlrev_b32_e32 v163, 16, v153
	v_and_b32_e32 v153, 0xffff0000, v153
	v_lshlrev_b32_e32 v164, 16, v154
	v_and_b32_e32 v154, 0xffff0000, v154
	v_lshlrev_b32_e32 v165, 16, v155
	v_and_b32_e32 v155, 0xffff0000, v155
	v_add_f32_e32 v133, v133, v152
	v_add_f32_e32 v151, v151, v153
	v_add_f32_e32 v160, v160, v154
	v_add_f32_e32 v161, v161, v155
	ds_read_b128 v[152:155], v149 offset:7312
	v_add_f32_e32 v158, v158, v162
	v_add_f32_e32 v159, v159, v163
	v_add_f32_e32 v156, v156, v164
	v_add_f32_e32 v157, v157, v165
	s_waitcnt lgkmcnt(0)
	v_lshlrev_b32_e32 v162, 16, v152
	v_and_b32_e32 v152, 0xffff0000, v152
	v_lshlrev_b32_e32 v163, 16, v153
	v_and_b32_e32 v153, 0xffff0000, v153
	v_lshlrev_b32_e32 v164, 16, v154
	v_and_b32_e32 v154, 0xffff0000, v154
	v_lshlrev_b32_e32 v165, 16, v155
	v_and_b32_e32 v155, 0xffff0000, v155
	v_add_f32_e32 v133, v133, v152
	v_add_f32_e32 v151, v151, v153
	v_add_f32_e32 v160, v160, v154
	v_add_f32_e32 v161, v161, v155
	ds_read_b128 v[152:155], v149 offset:7840
	v_add_f32_e32 v158, v158, v162
	v_add_f32_e32 v159, v159, v163
	v_add_f32_e32 v156, v156, v164
	v_add_f32_e32 v157, v157, v165
	s_waitcnt lgkmcnt(0)
	v_lshlrev_b32_e32 v162, 16, v152
	v_and_b32_e32 v152, 0xffff0000, v152
	v_lshlrev_b32_e32 v163, 16, v153
	v_and_b32_e32 v153, 0xffff0000, v153
	v_lshlrev_b32_e32 v164, 16, v154
	v_and_b32_e32 v154, 0xffff0000, v154
	v_lshlrev_b32_e32 v165, 16, v155
	v_and_b32_e32 v155, 0xffff0000, v155
	v_add_f32_e32 v133, v133, v152
	v_add_f32_e32 v151, v151, v153
	v_add_f32_e32 v160, v160, v154
	v_add_f32_e32 v161, v161, v155
	ds_read_b128 v[152:155], v149 offset:8368
	v_add_f32_e32 v158, v158, v162
	v_add_f32_e32 v159, v159, v163
	v_add_f32_e32 v156, v156, v164
	v_add_f32_e32 v157, v157, v165
	s_waitcnt lgkmcnt(0)
	v_lshlrev_b32_e32 v162, 16, v152
	v_and_b32_e32 v152, 0xffff0000, v152
	v_lshlrev_b32_e32 v163, 16, v153
	v_and_b32_e32 v153, 0xffff0000, v153
	v_lshlrev_b32_e32 v164, 16, v154
	v_and_b32_e32 v154, 0xffff0000, v154
	v_lshlrev_b32_e32 v165, 16, v155
	v_and_b32_e32 v155, 0xffff0000, v155
	v_add_f32_e32 v158, v158, v162
	v_add_f32_e32 v133, v133, v152
	v_add_f32_e32 v152, v159, v163
	v_add_f32_e32 v151, v151, v153
	v_add_f32_e32 v153, v156, v164
	v_add_f32_e32 v154, v160, v154
	v_add_f32_e32 v156, v157, v165
	v_add_f32_e32 v155, v161, v155
	v_fma_f32 v57, v56, v158, -v57
	v_fma_f32 v58, v56, v133, -v58
	v_fma_f32 v59, v56, v152, -v59
	v_fma_f32 v60, v56, v151, -v60
	v_fma_f32 v61, v56, v153, -v61
	v_fma_f32 v62, v56, v154, -v62
	v_fma_f32 v63, v56, v156, -v63
	v_fma_f32 v56, v56, v155, -v131
	v_cvt_pk_bf16_f32 v152, v57, v58
	v_cvt_pk_bf16_f32 v153, v59, v60
	v_cvt_pk_bf16_f32 v154, v61, v62
	v_cvt_pk_bf16_f32 v155, v63, v56
	s_waitcnt vmcnt(0)
	v_mfma_f32_16x16x32_bf16 v[60:63], v[222:225], v[152:155], v[48:51]
	s_nop 2
	v_mov_b32_e32 v133, v209
	s_waitcnt vmcnt(0)
	v_mfma_f32_16x16x32_bf16 v[56:59], v[226:229], v[152:155], v[52:55]
	s_waitcnt vmcnt(0)
	v_mfma_f32_16x16x32_bf16 v[52:55], v[230:233], v[152:155], v[64:67]
	s_nop 1
	v_pk_mul_f32 v[64:65], v[14:15], v[14:15]
	v_pk_mul_f32 v[66:67], v[12:13], v[12:13]
	s_waitcnt vmcnt(0)
	v_mfma_f32_16x16x32_bf16 v[48:51], v[234:237], v[152:155], v[68:71]
	s_nop 2
	v_pk_mov_b32 v[68:69], v[66:67], v[64:65] op_sel:[1,0]
	v_mov_b32_e32 v67, v65
	v_pk_add_f32 v[64:65], v[68:69], v[66:67]
	v_pk_mul_f32 v[66:67], v[10:11], v[10:11]
	v_pk_mul_f32 v[68:69], v[8:9], v[8:9]
	v_pk_add_f32 v[64:65], v[64:65], v[64:65] op_sel:[0,1] op_sel_hi:[1,0]
	v_pk_mov_b32 v[70:71], v[68:69], v[66:67] op_sel:[1,0]
	v_mov_b32_e32 v69, v67
	v_pk_add_f32 v[66:67], v[70:71], v[68:69]
	v_mul_f32_e32 v68, v0, v0
	v_mul_f32_e32 v69, v1, v1
	v_pk_add_f32 v[66:67], v[66:67], v[66:67] op_sel:[0,1] op_sel_hi:[1,0]
	v_mov_b32_e32 v65, v68
	v_mov_b32_e32 v67, v69
	v_pk_add_f32 v[64:65], v[64:65], v[66:67]
	v_mul_f32_e32 v66, v5, v5
	v_mul_f32_e32 v68, v7, v7
	v_mul_f32_e32 v70, v2, v2
	v_mul_f32_e32 v71, v3, v3
	v_pk_fma_f32 v[66:67], v[4:5], v[4:5], v[66:67] op_sel_hi:[1,1,0]
	v_pk_fma_f32 v[68:69], v[6:7], v[6:7], v[68:69] op_sel_hi:[1,1,0]
	v_mov_b32_e32 v67, v70
	v_mov_b32_e32 v69, v71
	v_pk_add_f32 v[66:67], v[66:67], v[68:69]
	v_pk_mul_f32 v[68:69], v[28:29], v[28:29]
	v_pk_add_f32 v[64:65], v[64:65], v[66:67]
	v_pk_mul_f32 v[66:67], v[30:31], v[30:31]
	v_pk_add_f32 v[64:65], v[64:65], v[64:65] op_sel:[0,1] op_sel_hi:[1,0]
	v_pk_mov_b32 v[70:71], v[68:69], v[66:67] op_sel:[1,0]
	v_mov_b32_e32 v69, v67
	v_pk_add_f32 v[66:67], v[70:71], v[68:69]
	v_mul_f32_e32 v68, v20, v20
	v_mul_f32_e32 v69, v21, v21
	v_pk_add_f32 v[66:67], v[66:67], v[66:67] op_sel:[0,1] op_sel_hi:[1,0]
	v_mov_b32_e32 v65, v68
	v_mov_b32_e32 v67, v69
	v_pk_add_f32 v[64:65], v[64:65], v[66:67]
	v_mul_f32_e32 v66, v25, v25
	v_mul_f32_e32 v68, v27, v27
	v_mul_f32_e32 v70, v22, v22
	v_mul_f32_e32 v71, v23, v23
	v_pk_fma_f32 v[66:67], v[24:25], v[24:25], v[66:67] op_sel_hi:[1,1,0]
	v_pk_fma_f32 v[68:69], v[26:27], v[26:27], v[68:69] op_sel_hi:[1,1,0]
	v_mov_b32_e32 v67, v70
	v_mov_b32_e32 v69, v71
	v_pk_add_f32 v[66:67], v[66:67], v[68:69]
	v_pk_mul_f32 v[68:69], v[16:17], v[16:17]
	v_pk_add_f32 v[64:65], v[64:65], v[66:67]
	v_pk_mul_f32 v[66:67], v[18:19], v[18:19]
	v_pk_add_f32 v[64:65], v[64:65], v[64:65] op_sel:[0,1] op_sel_hi:[1,0]
	v_pk_mov_b32 v[70:71], v[68:69], v[66:67] op_sel:[1,0]
	v_mov_b32_e32 v69, v67
	v_pk_add_f32 v[66:67], v[70:71], v[68:69]
	v_mul_f32_e32 v68, v40, v40
	v_mul_f32_e32 v69, v41, v41
	v_pk_add_f32 v[66:67], v[66:67], v[66:67] op_sel:[0,1] op_sel_hi:[1,0]
	v_mov_b32_e32 v65, v68
	v_mov_b32_e32 v67, v69
	v_pk_add_f32 v[64:65], v[64:65], v[66:67]
	v_mul_f32_e32 v66, v45, v45
	v_mul_f32_e32 v68, v47, v47
	v_mul_f32_e32 v70, v42, v42
	v_mul_f32_e32 v71, v43, v43
	v_pk_fma_f32 v[66:67], v[44:45], v[44:45], v[66:67] op_sel_hi:[1,1,0]
	v_pk_fma_f32 v[68:69], v[46:47], v[46:47], v[68:69] op_sel_hi:[1,1,0]
	v_mov_b32_e32 v67, v70
	v_mov_b32_e32 v69, v71
	v_pk_add_f32 v[66:67], v[66:67], v[68:69]
	v_pk_mul_f32 v[68:69], v[36:37], v[36:37]
	v_pk_add_f32 v[64:65], v[64:65], v[66:67]
	v_pk_mul_f32 v[66:67], v[38:39], v[38:39]
	v_pk_add_f32 v[64:65], v[64:65], v[64:65] op_sel:[0,1] op_sel_hi:[1,0]
	v_pk_mov_b32 v[70:71], v[68:69], v[66:67] op_sel:[1,0]
	v_mov_b32_e32 v69, v67
	v_pk_add_f32 v[66:67], v[70:71], v[68:69]
	v_mul_f32_e32 v68, v60, v60
	v_mul_f32_e32 v69, v61, v61
	v_pk_add_f32 v[66:67], v[66:67], v[66:67] op_sel:[0,1] op_sel_hi:[1,0]
	v_mov_b32_e32 v65, v68
	v_mov_b32_e32 v67, v69
	v_pk_add_f32 v[64:65], v[64:65], v[66:67]
	v_mul_f32_e32 v66, v33, v33
	v_mul_f32_e32 v68, v35, v35
	v_mul_f32_e32 v70, v62, v62
	v_mul_f32_e32 v71, v63, v63
	v_pk_fma_f32 v[66:67], v[32:33], v[32:33], v[66:67] op_sel_hi:[1,1,0]
	v_pk_fma_f32 v[68:69], v[34:35], v[34:35], v[68:69] op_sel_hi:[1,1,0]
	v_mov_b32_e32 v67, v70
	v_mov_b32_e32 v69, v71
	v_pk_add_f32 v[66:67], v[66:67], v[68:69]
	v_pk_mul_f32 v[68:69], v[56:57], v[56:57]
	v_pk_add_f32 v[64:65], v[64:65], v[66:67]
	v_pk_mul_f32 v[66:67], v[58:59], v[58:59]
	v_pk_add_f32 v[64:65], v[64:65], v[64:65] op_sel:[0,1] op_sel_hi:[1,0]
	v_pk_mov_b32 v[70:71], v[68:69], v[66:67] op_sel:[1,0]
	v_mov_b32_e32 v69, v67
	v_pk_add_f32 v[66:67], v[70:71], v[68:69]
	v_mul_f32_e32 v68, v48, v48
	v_mul_f32_e32 v69, v49, v49
	v_pk_add_f32 v[66:67], v[66:67], v[66:67] op_sel:[0,1] op_sel_hi:[1,0]
	v_mov_b32_e32 v65, v68
	v_mov_b32_e32 v67, v69
	v_pk_add_f32 v[64:65], v[64:65], v[66:67]
	v_mul_f32_e32 v66, v53, v53
	v_mul_f32_e32 v68, v55, v55
	v_mul_f32_e32 v70, v50, v50
	v_mul_f32_e32 v71, v51, v51
	v_pk_fma_f32 v[66:67], v[52:53], v[52:53], v[66:67] op_sel_hi:[1,1,0]
	v_pk_fma_f32 v[68:69], v[54:55], v[54:55], v[68:69] op_sel_hi:[1,1,0]
	v_mov_b32_e32 v67, v70
	v_mov_b32_e32 v69, v71
	v_pk_add_f32 v[66:67], v[66:67], v[68:69]
	v_and_b32_e32 v68, 64, v245
	v_pk_add_f32 v[64:65], v[64:65], v[66:67]
	v_xor_b32_e32 v67, 16, v245
	v_add_u32_e32 v68, 64, v68
	v_cmp_lt_i32_e32 vcc, v67, v68
	v_add_f32_e32 v66, v64, v65
	v_lshl_add_u64 v[64:65], s[84:85], 0, v[134:135]
	v_cndmask_b32_e32 v67, v245, v67, vcc
	v_lshlrev_b32_e32 v67, 2, v67
	ds_bpermute_b32 v67, v67, v66
	v_lshl_add_u64 v[64:65], v[64:65], 0, v[132:133]
	s_waitcnt lgkmcnt(0)
	v_add_f32_e32 v66, v66, v67
	v_xor_b32_e32 v67, 32, v245
	v_cmp_lt_i32_e32 vcc, v67, v68
	v_lshl_add_u64 v[68:69], v[64:65], 0, s[18:19]
	s_nop 0
	v_cndmask_b32_e32 v67, v245, v67, vcc
	v_lshlrev_b32_e32 v67, 2, v67
	ds_bpermute_b32 v67, v67, v66
	s_waitcnt lgkmcnt(0)
	v_add_f32_e32 v66, v66, v67
	v_fmamk_f32 v66, v66, 0x3b800000, v244
	v_cmp_gt_f32_e32 vcc, s7, v66
	v_mul_f32_e32 v67, 0x4b800000, v66
	s_nop 0
	v_cndmask_b32_e32 v66, v66, v67, vcc
	v_rsq_f32_e32 v66, v66
	s_nop 0
	v_mul_f32_e32 v67, 0x45800000, v66
	v_cndmask_b32_e32 v66, v66, v67, vcc
	v_mul_f32_e32 v12, v12, v66
	v_mul_f32_e32 v13, v13, v66
	v_cvt_pk_bf16_f32 v12, v12, v13
	v_mul_f32_e32 v13, v14, v66
	v_mul_f32_e32 v14, v15, v66
	v_cvt_pk_bf16_f32 v13, v13, v14
	v_add_co_u32_e32 v14, vcc, s47, v64
	v_mul_f32_e32 v8, v8, v66
	s_nop 0
	v_addc_co_u32_e32 v15, vcc, 0, v65, vcc
	v_mul_f32_e32 v9, v9, v66
	global_store_dwordx2 v[14:15], v[12:13], off offset:512
	v_cvt_pk_bf16_f32 v8, v8, v9
	v_mul_f32_e32 v9, v10, v66
	v_mul_f32_e32 v4, v4, v66
	v_mul_f32_e32 v5, v5, v66
	v_mul_f32_e32 v10, v11, v66
	v_cvt_pk_bf16_f32 v9, v9, v10
	global_store_dwordx2 v[68:69], v[8:9], off offset:32
	v_cvt_pk_bf16_f32 v4, v4, v5
	v_mul_f32_e32 v5, v6, v66
	v_mul_f32_e32 v0, v0, v66
	v_mul_f32_e32 v1, v1, v66
	v_mul_f32_e32 v6, v7, v66
	v_cvt_pk_bf16_f32 v5, v5, v6
	global_store_dwordx2 v[68:69], v[4:5], off offset:64
	v_cvt_pk_bf16_f32 v0, v0, v1
	v_mul_f32_e32 v1, v2, v66
	v_mul_f32_e32 v2, v3, v66
	v_cvt_pk_bf16_f32 v1, v1, v2
	global_store_dwordx2 v[68:69], v[0:1], off offset:96
	v_mul_f32_e32 v0, v28, v66
	v_mul_f32_e32 v1, v29, v66
	v_cvt_pk_bf16_f32 v0, v0, v1
	v_mul_f32_e32 v1, v30, v66
	v_mul_f32_e32 v2, v31, v66
	v_cvt_pk_bf16_f32 v1, v1, v2
	global_store_dwordx2 v[68:69], v[0:1], off offset:128
	v_mul_f32_e32 v0, v24, v66
	v_mul_f32_e32 v1, v25, v66
	v_cvt_pk_bf16_f32 v0, v0, v1
	v_mul_f32_e32 v1, v26, v66
	v_mul_f32_e32 v2, v27, v66
	v_cvt_pk_bf16_f32 v1, v1, v2
	global_store_dwordx2 v[68:69], v[0:1], off offset:160
	v_mul_f32_e32 v0, v20, v66
	v_mul_f32_e32 v1, v21, v66
	v_cvt_pk_bf16_f32 v0, v0, v1
	v_mul_f32_e32 v1, v22, v66
	v_mul_f32_e32 v2, v23, v66
	v_cvt_pk_bf16_f32 v1, v1, v2
	global_store_dwordx2 v[68:69], v[0:1], off offset:192
	v_mul_f32_e32 v0, v16, v66
	v_mul_f32_e32 v1, v17, v66
	v_cvt_pk_bf16_f32 v0, v0, v1
	v_mul_f32_e32 v1, v18, v66
	v_mul_f32_e32 v2, v19, v66
	v_cvt_pk_bf16_f32 v1, v1, v2
	global_store_dwordx2 v[68:69], v[0:1], off offset:224
	v_mul_f32_e32 v0, v44, v66
	v_mul_f32_e32 v1, v45, v66
	v_cvt_pk_bf16_f32 v0, v0, v1
	v_mul_f32_e32 v1, v46, v66
	v_mul_f32_e32 v2, v47, v66
	v_cvt_pk_bf16_f32 v1, v1, v2
	global_store_dwordx2 v[68:69], v[0:1], off offset:256
	v_mul_f32_e32 v0, v40, v66
	v_mul_f32_e32 v1, v41, v66
	v_cvt_pk_bf16_f32 v0, v0, v1
	v_mul_f32_e32 v1, v42, v66
	v_mul_f32_e32 v2, v43, v66
	v_cvt_pk_bf16_f32 v1, v1, v2
	global_store_dwordx2 v[68:69], v[0:1], off offset:288
	v_mul_f32_e32 v0, v36, v66
	v_mul_f32_e32 v1, v37, v66
	v_cvt_pk_bf16_f32 v0, v0, v1
	v_mul_f32_e32 v1, v38, v66
	v_mul_f32_e32 v2, v39, v66
	v_cvt_pk_bf16_f32 v1, v1, v2
	global_store_dwordx2 v[68:69], v[0:1], off offset:320
	v_mul_f32_e32 v0, v32, v66
	v_mul_f32_e32 v1, v33, v66
	v_cvt_pk_bf16_f32 v0, v0, v1
	v_mul_f32_e32 v1, v34, v66
	v_mul_f32_e32 v2, v35, v66
	v_cvt_pk_bf16_f32 v1, v1, v2
	global_store_dwordx2 v[68:69], v[0:1], off offset:352
	v_mul_f32_e32 v0, v60, v66
	v_mul_f32_e32 v1, v61, v66
	v_cvt_pk_bf16_f32 v0, v0, v1
	v_mul_f32_e32 v1, v62, v66
	v_mul_f32_e32 v2, v63, v66
	v_cvt_pk_bf16_f32 v1, v1, v2
	global_store_dwordx2 v[68:69], v[0:1], off offset:384
	v_mul_f32_e32 v0, v56, v66
	v_mul_f32_e32 v1, v57, v66
	v_cvt_pk_bf16_f32 v0, v0, v1
	v_mul_f32_e32 v1, v58, v66
	v_mul_f32_e32 v2, v59, v66
	v_cvt_pk_bf16_f32 v1, v1, v2
	global_store_dwordx2 v[68:69], v[0:1], off offset:416
	v_mul_f32_e32 v0, v52, v66
	v_mul_f32_e32 v1, v53, v66
	v_cvt_pk_bf16_f32 v0, v0, v1
	v_mul_f32_e32 v1, v54, v66
	v_mul_f32_e32 v2, v55, v66
	v_cvt_pk_bf16_f32 v1, v1, v2
	global_store_dwordx2 v[68:69], v[0:1], off offset:448
	v_mul_f32_e32 v0, v48, v66
	v_mul_f32_e32 v1, v49, v66
	v_cvt_pk_bf16_f32 v0, v0, v1
	v_mul_f32_e32 v1, v50, v66
	v_mul_f32_e32 v2, v51, v66
	v_cvt_pk_bf16_f32 v1, v1, v2
	global_store_dwordx2 v[68:69], v[0:1], off offset:480
	s_waitcnt lgkmcnt(0)
	s_cbranch_scc1 .LBB0_235
	v_readlane_b32 s16, v253, 49
	s_mov_b64 s[36:37], 0xc000800
